# ssd_stage conv loops (passA+passB): 5x unrolled row-buffer ring, counted vmcnt(3) keeps 4 row loads in flight instead of waiting for the newest load each iteration
# baseline (speedup 1.0000x reference)
; __device__ __forceinline__ void unpack8(const u32x4 w, float* f) { f[0] = bflo(w.x); f[1] = bfhi(w.x); f[2] = bflo(w.y); f[3] = bfhi(w.y); f[4] = bflo(w.z); f[5] = bfhi(w.z); f[6] = bflo(w.w); f[7] = bfhi(w.w); }
; #define SSD_LD(tt) ((live && (tt) >= 0) ? *(const u32x4*)(PJ + (size_t)tok_row(b, (tt)) * PW + C_XBC + xcol) : (u32x4){0u, 0u, 0u, 0u})
; template <bool PASSA> __device__ __forceinline__ void ssd_stage(const Ptrs& P, int l, int b, int ch, int gg, unsigned char* lds, int tid) {
;     ...
;         const int t0 = (ch == 0) ? l0 : (NMETA + 128 * (ch - 1) + l0);
;         float x0[8], x1[8], x2[8], x3[8];
;         const bool live = l0 < nvalid;
;     ...
;         { const u32x4 h0 = SSD_LD(t0 - 3), h1 = SSD_LD(t0 - 2), h2 = SSD_LD(t0 - 1); unpack8(h0, x0); unpack8(h1, x1); unpack8(h2, x2); }
;         u32x4 n0 = SSD_LD(t0), n1 = SSD_LD(t0 + 1), n2 = SSD_LD(t0 + 2), n3 = SSD_LD(t0 + 3);
; #pragma unroll 1
;         for (int i = 0; i < 16; ++i) {
;             const int li = l0 + i;
;             unpack8(n0, x3); n0 = n1; n1 = n2; n2 = n3; n3 = (i + 4 < 16) ? SSD_LD(t0 + i + 4) : (u32x4){0u, 0u, 0u, 0u};
.LBB0_482:
	s_or_b64 exec, exec, s[8:9]
	v_readlane_b32 s10, v255, 25
	s_waitcnt vmcnt(0)
	v_lshlrev_b32_e32 v19, 16, v81
	v_and_b32_e32 v125, 0xffff0000, v81
	s_lshl_b32 s9, s13, 4
	v_mov_b32_e32 v81, s10
	s_lshl_b32 s8, s13, 14
	v_cndmask_b32_e64 v81, v81, 0, s[38:39]
	s_add_i32 s9, s17, s9
	v_lshlrev_b32_e32 v145, 16, v68
	v_and_b32_e32 v144, 0xffff0000, v68
	v_lshlrev_b32_e32 v143, 16, v69
	v_and_b32_e32 v142, 0xffff0000, v69
	v_lshlrev_b32_e32 v141, 16, v70
	v_and_b32_e32 v140, 0xffff0000, v70
	v_lshlrev_b32_e32 v139, 16, v71
	v_and_b32_e32 v132, 0xffff0000, v71
	v_add_u32_e32 v68, 1, v104
	v_add_u32_e32 v69, 2, v104
	v_add_u32_e32 v70, 3, v104
	v_add_u32_e32 v71, 4, v104
	v_add_u32_e32 v117, 5, v104
	v_add_u32_e32 v119, 6, v104
	v_add_u32_e32 v121, 7, v104
	v_mad_i32_i24 v81, v104, s26, v81
	s_add_i32 s9, s9, 0x8004
	s_add_i32 s17, s17, s8
	v_lshlrev_b32_e32 v105, 16, v76
	v_and_b32_e32 v76, 0xffff0000, v76
	v_lshlrev_b32_e32 v109, 16, v77
	v_and_b32_e32 v77, 0xffff0000, v77
	v_lshlrev_b32_e32 v110, 16, v78
	v_and_b32_e32 v78, 0xffff0000, v78
	v_lshlrev_b32_e32 v111, 16, v79
	v_and_b32_e32 v79, 0xffff0000, v79
	v_lshlrev_b32_e32 v17, 16, v80
	v_and_b32_e32 v18, 0xffff0000, v80
	v_lshlrev_b32_e32 v126, 16, v82
	v_and_b32_e32 v127, 0xffff0000, v82
	v_lshlrev_b32_e32 v128, 16, v83
	v_and_b32_e32 v129, 0xffff0000, v83
	v_and_b32_e32 v80, 0x78, v104
	v_and_b32_e32 v82, 0x78, v68
	v_add_u32_e32 v83, 0x110, v81
	v_and_b32_e32 v104, 0x78, v69
	v_add_u32_e32 v112, 0x220, v81
	v_and_b32_e32 v113, 0x78, v70
	v_add_u32_e32 v114, 0x330, v81
	v_and_b32_e32 v115, 0x78, v71
	v_add_u32_e32 v116, 0x440, v81
	v_and_b32_e32 v117, 0x78, v117
	v_add_u32_e32 v118, 0x550, v81
	v_and_b32_e32 v119, 0x78, v119
	v_add_u32_e32 v120, 0x660, v81
	v_and_b32_e32 v121, 0x78, v121
	v_add_u32_e32 v122, 0x770, v81
	v_add_u32_e32 v123, s9, v102
	v_add3_u32 v124, s17, -12, v102
	s_mov_b32 s17, 0
	s_branch .Lsa_top_0
.Lsa_top_0:
	v_mov_b32_e32 v136, v109
	v_mov_b32_e32 v137, v76
	v_mov_b32_e32 v76, v18
	v_mov_b32_e32 v109, v19
	s_cmp_lt_u32 s17, 12
	v_mov_b32_e32 v18, v16
	v_mov_b32_e32 v19, v16
	v_mov_b32_e32 v138, v105
	v_mov_b32_e32 v105, v17
	s_cselect_b64 s[8:9], -1, 0
	v_mov_b32_e32 v17, v16
	v_mov_b64_e32 v[70:71], v[18:19]
	v_mov_b32_e32 v130, v79
	v_mov_b32_e32 v131, v111
	v_mov_b32_e32 v133, v78
	v_mov_b32_e32 v134, v110
	v_mov_b32_e32 v135, v77
	v_mov_b32_e32 v77, v125
	v_mov_b32_e32 v110, v126
	v_mov_b32_e32 v78, v127
	v_mov_b32_e32 v111, v128
	v_mov_b32_e32 v79, v129
	s_and_b64 s[10:11], s[40:41], s[8:9]
	v_mov_b64_e32 v[68:69], v[16:17]
	s_and_saveexec_b64 s[8:9], s[10:11]
	s_cbranch_execz .Lsa0_484
	v_mov_b32_e32 v18, v16
	v_mov_b32_e32 v19, v16
	v_add_u32_e32 v125, s17, v103
	v_mov_b32_e32 v17, v16
	v_mov_b64_e32 v[70:71], v[18:19]
	v_cmp_lt_i32_e32 vcc, -5, v125
	v_mov_b64_e32 v[68:69], v[16:17]
	s_and_saveexec_b64 s[10:11], vcc
	s_cbranch_execz .Lsa0_483
	v_add_u32_e32 v17, 4, v125
	v_cmp_gt_u32_e32 vcc, 16, v17
	s_nop 1
	v_cndmask_b32_e32 v17, v124, v123, vcc
	v_add_u32_e32 v17, s17, v17
	v_mad_i64_i32 v[18:19], s[18:19], v17, s34, v[86:87]
	v_lshl_add_u64 v[18:19], v[100:101], 1, v[18:19]
	v_add_co_u32_e32 v18, vcc, 0x1000, v18
	s_nop 1
	v_addc_co_u32_e32 v19, vcc, 0, v19, vcc
	global_load_dwordx4 v[68:71], v[18:19], off offset:2560
	s_branch .Lsa0_483
.Lsa0_483:
	s_or_b64 exec, exec, s[10:11]
; __device__ __forceinline__ unsigned f2bf(float f) { return pk2(f, 0.f) & 0xffffu; }
; __device__ __forceinline__ float siluf(float x) { return x * __builtin_amdgcn_rcpf(1.0f + __expf(-x)); }
; __device__ __forceinline__ void unpack8(const u32x4 w, float* f) { f[0] = bflo(w.x); f[1] = bfhi(w.x); f[2] = bflo(w.y); f[3] = bfhi(w.y); f[4] = bflo(w.z); f[5] = bfhi(w.z); f[6] = bflo(w.w); f[7] = bfhi(w.w); }
; #define SSD_LD(tt) ((live && (tt) >= 0) ? *(const u32x4*)(PJ + (size_t)tok_row(b, (tt)) * PW + C_XBC + xcol) : (u32x4){0u, 0u, 0u, 0u})
; template <bool PASSA> __device__ __forceinline__ void ssd_stage(const Ptrs& P, int l, int b, int ch, int gg, unsigned char* lds, int tid) {
;     ...
;         for (int i = 0; i < 16; ++i) {
;             const int li = l0 + i;
;             unpack8(n0, x3); n0 = n1; n1 = n2; n2 = n3; n3 = (i + 4 < 16) ? SSD_LD(t0 + i + 4) : (u32x4){0u, 0u, 0u, 0u};
;             float o[8];
; #pragma unroll
;             for (int e = 0; e < 8; ++e) { float v = bias[e] + wgt[0][e] * x0[e] + wgt[1][e] * x1[e] + wgt[2][e] * x2[e] + wgt[3][e] * x3[e]; v = siluf(v); o[e] = (li < nvalid) ? v : 0.f;
;                 x0[e] = x1[e]; x1[e] = x2[e]; x2[e] = x3[e]; }
;             if (kind == 0) {
; #pragma unroll
;                 for (int e = 0; e < 8; ++e) Xt[sdz(i0 + e, li)] = (bf16_t)f2bf(o[e]);
;             } else if (kind == 1) {
;                 if (PASSA) {
; #pragma unroll
;                     for (int e = 0; e < 8; ++e) Bs[sdz(i0 + e, li)] = (bf16_t)f2bf(o[e]);
.Lsa0_484:
	s_or_b64 exec, exec, s[8:9]
	v_lshlrev_b32_e32 v17, 16, v72
	v_and_b32_e32 v18, 0xffff0000, v72
	v_fma_f32 v72, v20, v145, v52
	v_fmac_f32_e32 v72, v24, v138
	v_fmac_f32_e32 v72, v32, v105
	v_fmac_f32_e32 v72, v40, v17
	v_lshlrev_b32_e32 v19, 16, v73
	v_and_b32_e32 v125, 0xffff0000, v73
	v_mul_f32_e32 v73, 0xbfb8aa3b, v72
	v_exp_f32_e32 v73, v73
	v_lshlrev_b32_e32 v126, 16, v74
	v_and_b32_e32 v127, 0xffff0000, v74
	v_lshlrev_b32_e32 v128, 16, v75
	v_add_f32_e32 v73, 1.0, v73
	v_rcp_f32_e32 v73, v73
	v_and_b32_e32 v129, 0xffff0000, v75
	v_fma_f32 v141, v10, v141, v48
	v_fmac_f32_e32 v141, v28, v134
	v_mul_f32_e32 v72, v72, v73
	v_fma_f32 v73, v21, v144, v53
	v_fmac_f32_e32 v73, v25, v137
	v_fmac_f32_e32 v73, v33, v76
	v_fmac_f32_e32 v73, v41, v18
	v_mul_f32_e32 v74, 0xbfb8aa3b, v73
	v_exp_f32_e32 v74, v74
	v_fmac_f32_e32 v141, v36, v110
	v_fmac_f32_e32 v141, v44, v126
	v_fma_f32 v140, v11, v140, v49
	v_add_f32_e32 v74, 1.0, v74
	v_rcp_f32_e32 v74, v74
	v_fmac_f32_e32 v140, v29, v133
	v_fmac_f32_e32 v140, v37, v78
	v_fmac_f32_e32 v140, v45, v127
	v_mul_f32_e32 v73, v73, v74
	v_fma_f32 v74, v22, v143, v54
	v_fmac_f32_e32 v74, v26, v136
	v_fmac_f32_e32 v74, v34, v109
	v_fmac_f32_e32 v74, v42, v19
	v_mul_f32_e32 v75, 0xbfb8aa3b, v74
	v_exp_f32_e32 v75, v75
	v_fma_f32 v139, v12, v139, v50
	v_fmac_f32_e32 v139, v30, v131
	v_fmac_f32_e32 v139, v38, v111
	v_add_f32_e32 v75, 1.0, v75
	v_rcp_f32_e32 v75, v75
	v_fmac_f32_e32 v139, v46, v128
	v_fma_f32 v132, v13, v132, v51
	v_fmac_f32_e32 v132, v31, v130
	v_mul_f32_e32 v74, v74, v75
	v_fma_f32 v75, v23, v142, v55
	v_fmac_f32_e32 v75, v27, v135
	v_fmac_f32_e32 v75, v35, v77
	v_fmac_f32_e32 v75, v43, v125
	v_mul_f32_e32 v142, 0xbfb8aa3b, v75
	v_exp_f32_e32 v142, v142
	v_fmac_f32_e32 v132, v39, v79
	v_fmac_f32_e32 v132, v47, v129
	v_add_u32_e32 v146, s17, v102
	v_add_f32_e32 v142, 1.0, v142
	v_rcp_f32_e32 v142, v142
	v_cmp_gt_i32_e32 vcc, s15, v146
	v_cvt_pk_bf16_f32 v72, v72, s0
	v_cvt_pk_bf16_f32 v73, v73, s0
	v_mul_f32_e32 v75, v75, v142
	v_mul_f32_e32 v142, 0xbfb8aa3b, v141
	v_exp_f32_e32 v142, v142
	v_cndmask_b32_e32 v72, 0, v72, vcc
	v_cndmask_b32_e32 v73, 0, v73, vcc
	v_cvt_pk_bf16_f32 v74, v74, s0
	v_add_f32_e32 v142, 1.0, v142
	v_rcp_f32_e32 v142, v142
	v_cndmask_b32_e32 v74, 0, v74, vcc
	v_cvt_pk_bf16_f32 v75, v75, s0
	v_cndmask_b32_e32 v75, 0, v75, vcc
	v_mul_f32_e32 v141, v141, v142
	v_mul_f32_e32 v142, 0xbfb8aa3b, v140
	v_exp_f32_e32 v142, v142
	v_cvt_pk_bf16_f32 v141, v141, s0
	v_cndmask_b32_e32 v141, 0, v141, vcc
	s_add_i32 s17, s17, 1
	v_add_f32_e32 v142, 1.0, v142
	v_rcp_f32_e32 v142, v142
	s_cmp_lg_u32 s17, 16
	v_mov_b32_e32 v145, v138
	v_mov_b32_e32 v144, v137
	v_mul_f32_e32 v140, v140, v142
	v_mul_f32_e32 v142, 0xbfb8aa3b, v139
	v_exp_f32_e32 v142, v142
	v_cvt_pk_bf16_f32 v140, v140, s0
	v_cndmask_b32_e32 v140, 0, v140, vcc
	v_mov_b32_e32 v143, v136
	v_add_f32_e32 v142, 1.0, v142
	v_rcp_f32_e32 v142, v142
	s_nop 0
	v_mul_f32_e32 v139, v139, v142
	v_mul_f32_e32 v142, 0xbfb8aa3b, v132
	v_exp_f32_e32 v142, v142
	v_cvt_pk_bf16_f32 v139, v139, s0
	v_cndmask_b32_e32 v139, 0, v139, vcc
	v_add_f32_e32 v142, 1.0, v142
	v_rcp_f32_e32 v142, v142
	s_nop 0
	v_mul_f32_e32 v132, v132, v142
	v_xor_b32_e32 v142, v146, v80
	v_lshl_add_u32 v142, v142, 1, v81
	ds_write_b16 v142, v72
	v_xor_b32_e32 v72, v146, v82
	v_lshl_add_u32 v72, v72, 1, v83
	ds_write_b16 v72, v73
	v_xor_b32_e32 v72, v146, v104
	v_lshl_add_u32 v72, v72, 1, v112
	ds_write_b16 v72, v74
	v_xor_b32_e32 v72, v146, v113
	v_lshl_add_u32 v72, v72, 1, v114
	ds_write_b16 v72, v75
	v_xor_b32_e32 v72, v146, v115
	v_lshl_add_u32 v72, v72, 1, v116
	ds_write_b16 v72, v141
	v_xor_b32_e32 v72, v146, v117
	v_lshl_add_u32 v72, v72, 1, v118
	ds_write_b16 v72, v140
	v_xor_b32_e32 v72, v146, v119
	v_lshl_add_u32 v72, v72, 1, v120
	ds_write_b16 v72, v139
	v_cvt_pk_bf16_f32 v72, v132, s0
	v_xor_b32_e32 v73, v146, v121
	v_cndmask_b32_e32 v72, 0, v72, vcc
	v_lshl_add_u32 v73, v73, 1, v122
	ds_write_b16 v73, v72
	v_mov_b32_e32 v142, v135
	v_mov_b32_e32 v141, v134
	v_mov_b32_e32 v140, v133
	v_mov_b32_e32 v139, v131
	v_mov_b32_e32 v132, v130
	s_cmp_lt_u32 s17, 13
	s_cbranch_scc1 .Lsa_w3_0
	s_waitcnt vmcnt(0)
	s_cmp_lg_u32 s17, 16
	s_cbranch_scc0 .LBB0_489
	s_branch .Lsa_top_1
.Lsa_w3_0:
	s_waitcnt vmcnt(3)
.Lsa_top_1:
	v_mov_b32_e32 v136, v109
	v_mov_b32_e32 v137, v76
	v_mov_b32_e32 v76, v18
	v_mov_b32_e32 v109, v19
	s_cmp_lt_u32 s17, 12
	v_mov_b32_e32 v18, v16
	v_mov_b32_e32 v19, v16
	v_mov_b32_e32 v138, v105
	v_mov_b32_e32 v105, v17
	s_cselect_b64 s[8:9], -1, 0
	v_mov_b32_e32 v17, v16
	v_mov_b64_e32 v[74:75], v[18:19]
	v_mov_b32_e32 v130, v79
	v_mov_b32_e32 v131, v111
	v_mov_b32_e32 v133, v78
	v_mov_b32_e32 v134, v110
	v_mov_b32_e32 v135, v77
	v_mov_b32_e32 v77, v125
	v_mov_b32_e32 v110, v126
	v_mov_b32_e32 v78, v127
	v_mov_b32_e32 v111, v128
	v_mov_b32_e32 v79, v129
	s_and_b64 s[10:11], s[40:41], s[8:9]
	v_mov_b64_e32 v[72:73], v[16:17]
	s_and_saveexec_b64 s[8:9], s[10:11]
	s_cbranch_execz .Lsa1_484
	v_mov_b32_e32 v18, v16
	v_mov_b32_e32 v19, v16
	v_add_u32_e32 v125, s17, v103
	v_mov_b32_e32 v17, v16
	v_mov_b64_e32 v[74:75], v[18:19]
	v_cmp_lt_i32_e32 vcc, -5, v125
	v_mov_b64_e32 v[72:73], v[16:17]
	s_and_saveexec_b64 s[10:11], vcc
	s_cbranch_execz .Lsa1_483
	v_add_u32_e32 v17, 4, v125
	v_cmp_gt_u32_e32 vcc, 16, v17
	s_nop 1
	v_cndmask_b32_e32 v17, v124, v123, vcc
	v_add_u32_e32 v17, s17, v17
	v_mad_i64_i32 v[18:19], s[18:19], v17, s34, v[86:87]
	v_lshl_add_u64 v[18:19], v[100:101], 1, v[18:19]
	v_add_co_u32_e32 v18, vcc, 0x1000, v18
	s_nop 1
	v_addc_co_u32_e32 v19, vcc, 0, v19, vcc
	global_load_dwordx4 v[72:75], v[18:19], off offset:2560
	s_branch .Lsa1_483

; __device__ __forceinline__ unsigned f2bf(float f) { return pk2(f, 0.f) & 0xffffu; }
; __device__ __forceinline__ float siluf(float x) { return x * __builtin_amdgcn_rcpf(1.0f + __expf(-x)); }
; __device__ __forceinline__ void unpack8(const u32x4 w, float* f) { f[0] = bflo(w.x); f[1] = bfhi(w.x); f[2] = bflo(w.y); f[3] = bfhi(w.y); f[4] = bflo(w.z); f[5] = bfhi(w.z); f[6] = bflo(w.w); f[7] = bfhi(w.w); }
; #define SSD_LD(tt) ((live && (tt) >= 0) ? *(const u32x4*)(PJ + (size_t)tok_row(b, (tt)) * PW + C_XBC + xcol) : (u32x4){0u, 0u, 0u, 0u})
; template <bool PASSA> __device__ __forceinline__ void ssd_stage(const Ptrs& P, int l, int b, int ch, int gg, unsigned char* lds, int tid) {
;     ...
;         for (int i = 0; i < 16; ++i) {
;             const int li = l0 + i;
;             unpack8(n0, x3); n0 = n1; n1 = n2; n2 = n3; n3 = (i + 4 < 16) ? SSD_LD(t0 + i + 4) : (u32x4){0u, 0u, 0u, 0u};
;             float o[8];
; #pragma unroll
;             for (int e = 0; e < 8; ++e) { float v = bias[e] + wgt[0][e] * x0[e] + wgt[1][e] * x1[e] + wgt[2][e] * x2[e] + wgt[3][e] * x3[e]; v = siluf(v); o[e] = (li < nvalid) ? v : 0.f;
;                 x0[e] = x1[e]; x1[e] = x2[e]; x2[e] = x3[e]; }
;             if (kind == 0) {
; #pragma unroll
;                 for (int e = 0; e < 8; ++e) Xt[sdz(i0 + e, li)] = (bf16_t)f2bf(o[e]);
;             } else if (kind == 1) {
;                 if (PASSA) {
; #pragma unroll
;                     for (int e = 0; e < 8; ++e) Bs[sdz(i0 + e, li)] = (bf16_t)f2bf(o[e]);
.Lsa1_484:
	s_or_b64 exec, exec, s[8:9]
	v_lshlrev_b32_e32 v17, 16, v56
	v_and_b32_e32 v18, 0xffff0000, v56
	v_fma_f32 v56, v20, v145, v52
	v_fmac_f32_e32 v56, v24, v138
	v_fmac_f32_e32 v56, v32, v105
	v_fmac_f32_e32 v56, v40, v17
	v_lshlrev_b32_e32 v19, 16, v57
	v_and_b32_e32 v125, 0xffff0000, v57
	v_mul_f32_e32 v57, 0xbfb8aa3b, v56
	v_exp_f32_e32 v57, v57
	v_lshlrev_b32_e32 v126, 16, v58
	v_and_b32_e32 v127, 0xffff0000, v58
	v_lshlrev_b32_e32 v128, 16, v59
	v_add_f32_e32 v57, 1.0, v57
	v_rcp_f32_e32 v57, v57
	v_and_b32_e32 v129, 0xffff0000, v59
	v_fma_f32 v141, v10, v141, v48
	v_fmac_f32_e32 v141, v28, v134
	v_mul_f32_e32 v56, v56, v57
	v_fma_f32 v57, v21, v144, v53
	v_fmac_f32_e32 v57, v25, v137
	v_fmac_f32_e32 v57, v33, v76
	v_fmac_f32_e32 v57, v41, v18
	v_mul_f32_e32 v58, 0xbfb8aa3b, v57
	v_exp_f32_e32 v58, v58
	v_fmac_f32_e32 v141, v36, v110
	v_fmac_f32_e32 v141, v44, v126
	v_fma_f32 v140, v11, v140, v49
	v_add_f32_e32 v58, 1.0, v58
	v_rcp_f32_e32 v58, v58
	v_fmac_f32_e32 v140, v29, v133
	v_fmac_f32_e32 v140, v37, v78
	v_fmac_f32_e32 v140, v45, v127
	v_mul_f32_e32 v57, v57, v58
	v_fma_f32 v58, v22, v143, v54
	v_fmac_f32_e32 v58, v26, v136
	v_fmac_f32_e32 v58, v34, v109
	v_fmac_f32_e32 v58, v42, v19
	v_mul_f32_e32 v59, 0xbfb8aa3b, v58
	v_exp_f32_e32 v59, v59
	v_fma_f32 v139, v12, v139, v50
	v_fmac_f32_e32 v139, v30, v131
	v_fmac_f32_e32 v139, v38, v111
	v_add_f32_e32 v59, 1.0, v59
	v_rcp_f32_e32 v59, v59
	v_fmac_f32_e32 v139, v46, v128
	v_fma_f32 v132, v13, v132, v51
	v_fmac_f32_e32 v132, v31, v130
	v_mul_f32_e32 v58, v58, v59
	v_fma_f32 v59, v23, v142, v55
	v_fmac_f32_e32 v59, v27, v135
	v_fmac_f32_e32 v59, v35, v77
	v_fmac_f32_e32 v59, v43, v125
	v_mul_f32_e32 v142, 0xbfb8aa3b, v59
	v_exp_f32_e32 v142, v142
	v_fmac_f32_e32 v132, v39, v79
	v_fmac_f32_e32 v132, v47, v129
	v_add_u32_e32 v146, s17, v102
	v_add_f32_e32 v142, 1.0, v142
	v_rcp_f32_e32 v142, v142
	v_cmp_gt_i32_e32 vcc, s15, v146
	v_cvt_pk_bf16_f32 v56, v56, s0
	v_cvt_pk_bf16_f32 v57, v57, s0
	v_mul_f32_e32 v59, v59, v142
	v_mul_f32_e32 v142, 0xbfb8aa3b, v141
	v_exp_f32_e32 v142, v142
	v_cndmask_b32_e32 v56, 0, v56, vcc
	v_cndmask_b32_e32 v57, 0, v57, vcc
	v_cvt_pk_bf16_f32 v58, v58, s0
	v_add_f32_e32 v142, 1.0, v142
	v_rcp_f32_e32 v142, v142
	v_cndmask_b32_e32 v58, 0, v58, vcc
	v_cvt_pk_bf16_f32 v59, v59, s0
	v_cndmask_b32_e32 v59, 0, v59, vcc
	v_mul_f32_e32 v141, v141, v142
	v_mul_f32_e32 v142, 0xbfb8aa3b, v140
	v_exp_f32_e32 v142, v142
	v_cvt_pk_bf16_f32 v141, v141, s0
	v_cndmask_b32_e32 v141, 0, v141, vcc
	s_add_i32 s17, s17, 1
	v_add_f32_e32 v142, 1.0, v142
	v_rcp_f32_e32 v142, v142
	s_cmp_lg_u32 s17, 16
	v_mov_b32_e32 v145, v138
	v_mov_b32_e32 v144, v137
	v_mul_f32_e32 v140, v140, v142
	v_mul_f32_e32 v142, 0xbfb8aa3b, v139
	v_exp_f32_e32 v142, v142
	v_cvt_pk_bf16_f32 v140, v140, s0
	v_cndmask_b32_e32 v140, 0, v140, vcc
	v_mov_b32_e32 v143, v136
	v_add_f32_e32 v142, 1.0, v142
	v_rcp_f32_e32 v142, v142
	s_nop 0
	v_mul_f32_e32 v139, v139, v142
	v_mul_f32_e32 v142, 0xbfb8aa3b, v132
	v_exp_f32_e32 v142, v142
	v_cvt_pk_bf16_f32 v139, v139, s0
	v_cndmask_b32_e32 v139, 0, v139, vcc
	v_add_f32_e32 v142, 1.0, v142
	v_rcp_f32_e32 v142, v142
	s_nop 0
	v_mul_f32_e32 v132, v132, v142
	v_xor_b32_e32 v142, v146, v80
	v_lshl_add_u32 v142, v142, 1, v81
	ds_write_b16 v142, v56
	v_xor_b32_e32 v56, v146, v82
	v_lshl_add_u32 v56, v56, 1, v83
	ds_write_b16 v56, v57
	v_xor_b32_e32 v56, v146, v104
	v_lshl_add_u32 v56, v56, 1, v112
	ds_write_b16 v56, v58
	v_xor_b32_e32 v56, v146, v113
	v_lshl_add_u32 v56, v56, 1, v114
	ds_write_b16 v56, v59
	v_xor_b32_e32 v56, v146, v115
	v_lshl_add_u32 v56, v56, 1, v116
	ds_write_b16 v56, v141
	v_xor_b32_e32 v56, v146, v117
	v_lshl_add_u32 v56, v56, 1, v118
	ds_write_b16 v56, v140
	v_xor_b32_e32 v56, v146, v119
	v_lshl_add_u32 v56, v56, 1, v120
	ds_write_b16 v56, v139
	v_cvt_pk_bf16_f32 v56, v132, s0
	v_xor_b32_e32 v57, v146, v121
	v_cndmask_b32_e32 v56, 0, v56, vcc
	v_lshl_add_u32 v57, v57, 1, v122
	ds_write_b16 v57, v56
	v_mov_b32_e32 v142, v135
	v_mov_b32_e32 v141, v134
	v_mov_b32_e32 v140, v133
	v_mov_b32_e32 v139, v131
	v_mov_b32_e32 v132, v130
	s_cmp_lt_u32 s17, 13
	s_cbranch_scc1 .Lsa_w3_1
	s_waitcnt vmcnt(0)
	s_cmp_lg_u32 s17, 16
	s_cbranch_scc0 .LBB0_489
	s_branch .Lsa_top_2

; __device__ __forceinline__ void unpack8(const u32x4 w, float* f) { f[0] = bflo(w.x); f[1] = bfhi(w.x); f[2] = bflo(w.y); f[3] = bfhi(w.y); f[4] = bflo(w.z); f[5] = bfhi(w.z); f[6] = bflo(w.w); f[7] = bfhi(w.w); }
; #define SSD_LD(tt) ((live && (tt) >= 0) ? *(const u32x4*)(PJ + (size_t)tok_row(b, (tt)) * PW + C_XBC + xcol) : (u32x4){0u, 0u, 0u, 0u})
; template <bool PASSA> __device__ __forceinline__ void ssd_stage(const Ptrs& P, int l, int b, int ch, int gg, unsigned char* lds, int tid) {
;     ...
;         { const u32x4 h0 = SSD_LD(t0 - 3), h1 = SSD_LD(t0 - 2), h2 = SSD_LD(t0 - 1); unpack8(h0, x0); unpack8(h1, x1); unpack8(h2, x2); }
;         u32x4 n0 = SSD_LD(t0), n1 = SSD_LD(t0 + 1), n2 = SSD_LD(t0 + 2), n3 = SSD_LD(t0 + 3);
; #pragma unroll 1
;         for (int i = 0; i < 16; ++i) {
;             const int li = l0 + i;
;             unpack8(n0, x3); n0 = n1; n1 = n2; n2 = n3; n3 = (i + 4 < 16) ? SSD_LD(t0 + i + 4) : (u32x4){0u, 0u, 0u, 0u};
.Lsa_top_2:
	v_mov_b32_e32 v136, v109
	v_mov_b32_e32 v137, v76
	v_mov_b32_e32 v76, v18
	v_mov_b32_e32 v109, v19
	s_cmp_lt_u32 s17, 12
	v_mov_b32_e32 v18, v16
	v_mov_b32_e32 v19, v16
	v_mov_b32_e32 v138, v105
	v_mov_b32_e32 v105, v17
	s_cselect_b64 s[8:9], -1, 0
	v_mov_b32_e32 v17, v16
	v_mov_b64_e32 v[58:59], v[18:19]
	v_mov_b32_e32 v130, v79
	v_mov_b32_e32 v131, v111
	v_mov_b32_e32 v133, v78
	v_mov_b32_e32 v134, v110
	v_mov_b32_e32 v135, v77
	v_mov_b32_e32 v77, v125
	v_mov_b32_e32 v110, v126
	v_mov_b32_e32 v78, v127
	v_mov_b32_e32 v111, v128
	v_mov_b32_e32 v79, v129
	s_and_b64 s[10:11], s[40:41], s[8:9]
	v_mov_b64_e32 v[56:57], v[16:17]
	s_and_saveexec_b64 s[8:9], s[10:11]
	s_cbranch_execz .Lsa2_484
	v_mov_b32_e32 v18, v16
	v_mov_b32_e32 v19, v16
	v_add_u32_e32 v125, s17, v103
	v_mov_b32_e32 v17, v16
	v_mov_b64_e32 v[58:59], v[18:19]
	v_cmp_lt_i32_e32 vcc, -5, v125
	v_mov_b64_e32 v[56:57], v[16:17]
	s_and_saveexec_b64 s[10:11], vcc
	s_cbranch_execz .Lsa2_483
	v_add_u32_e32 v17, 4, v125
	v_cmp_gt_u32_e32 vcc, 16, v17
	s_nop 1
	v_cndmask_b32_e32 v17, v124, v123, vcc
	v_add_u32_e32 v17, s17, v17
	v_mad_i64_i32 v[18:19], s[18:19], v17, s34, v[86:87]
	v_lshl_add_u64 v[18:19], v[100:101], 1, v[18:19]
	v_add_co_u32_e32 v18, vcc, 0x1000, v18
	s_nop 1
	v_addc_co_u32_e32 v19, vcc, 0, v19, vcc
	global_load_dwordx4 v[56:59], v[18:19], off offset:2560
	s_branch .Lsa2_483

; __device__ __forceinline__ unsigned f2bf(float f) { return pk2(f, 0.f) & 0xffffu; }
; __device__ __forceinline__ float siluf(float x) { return x * __builtin_amdgcn_rcpf(1.0f + __expf(-x)); }
; __device__ __forceinline__ void unpack8(const u32x4 w, float* f) { f[0] = bflo(w.x); f[1] = bfhi(w.x); f[2] = bflo(w.y); f[3] = bfhi(w.y); f[4] = bflo(w.z); f[5] = bfhi(w.z); f[6] = bflo(w.w); f[7] = bfhi(w.w); }
; #define SSD_LD(tt) ((live && (tt) >= 0) ? *(const u32x4*)(PJ + (size_t)tok_row(b, (tt)) * PW + C_XBC + xcol) : (u32x4){0u, 0u, 0u, 0u})
; template <bool PASSA> __device__ __forceinline__ void ssd_stage(const Ptrs& P, int l, int b, int ch, int gg, unsigned char* lds, int tid) {
;     ...
;         for (int i = 0; i < 16; ++i) {
;             const int li = l0 + i;
;             unpack8(n0, x3); n0 = n1; n1 = n2; n2 = n3; n3 = (i + 4 < 16) ? SSD_LD(t0 + i + 4) : (u32x4){0u, 0u, 0u, 0u};
;             float o[8];
; #pragma unroll
;             for (int e = 0; e < 8; ++e) { float v = bias[e] + wgt[0][e] * x0[e] + wgt[1][e] * x1[e] + wgt[2][e] * x2[e] + wgt[3][e] * x3[e]; v = siluf(v); o[e] = (li < nvalid) ? v : 0.f;
;                 x0[e] = x1[e]; x1[e] = x2[e]; x2[e] = x3[e]; }
;             if (kind == 0) {
; #pragma unroll
;                 for (int e = 0; e < 8; ++e) Xt[sdz(i0 + e, li)] = (bf16_t)f2bf(o[e]);
;             } else if (kind == 1) {
;                 if (PASSA) {
; #pragma unroll
;                     for (int e = 0; e < 8; ++e) Bs[sdz(i0 + e, li)] = (bf16_t)f2bf(o[e]);
.Lsa2_484:
	s_or_b64 exec, exec, s[8:9]
	v_lshlrev_b32_e32 v17, 16, v60
	v_and_b32_e32 v18, 0xffff0000, v60
	v_fma_f32 v60, v20, v145, v52
	v_fmac_f32_e32 v60, v24, v138
	v_fmac_f32_e32 v60, v32, v105
	v_fmac_f32_e32 v60, v40, v17
	v_lshlrev_b32_e32 v19, 16, v61
	v_and_b32_e32 v125, 0xffff0000, v61
	v_mul_f32_e32 v61, 0xbfb8aa3b, v60
	v_exp_f32_e32 v61, v61
	v_lshlrev_b32_e32 v126, 16, v62
	v_and_b32_e32 v127, 0xffff0000, v62
	v_lshlrev_b32_e32 v128, 16, v63
	v_add_f32_e32 v61, 1.0, v61
	v_rcp_f32_e32 v61, v61
	v_and_b32_e32 v129, 0xffff0000, v63
	v_fma_f32 v141, v10, v141, v48
	v_fmac_f32_e32 v141, v28, v134
	v_mul_f32_e32 v60, v60, v61
	v_fma_f32 v61, v21, v144, v53
	v_fmac_f32_e32 v61, v25, v137
	v_fmac_f32_e32 v61, v33, v76
	v_fmac_f32_e32 v61, v41, v18
	v_mul_f32_e32 v62, 0xbfb8aa3b, v61
	v_exp_f32_e32 v62, v62
	v_fmac_f32_e32 v141, v36, v110
	v_fmac_f32_e32 v141, v44, v126
	v_fma_f32 v140, v11, v140, v49
	v_add_f32_e32 v62, 1.0, v62
	v_rcp_f32_e32 v62, v62
	v_fmac_f32_e32 v140, v29, v133
	v_fmac_f32_e32 v140, v37, v78
	v_fmac_f32_e32 v140, v45, v127
	v_mul_f32_e32 v61, v61, v62
	v_fma_f32 v62, v22, v143, v54
	v_fmac_f32_e32 v62, v26, v136
	v_fmac_f32_e32 v62, v34, v109
	v_fmac_f32_e32 v62, v42, v19
	v_mul_f32_e32 v63, 0xbfb8aa3b, v62
	v_exp_f32_e32 v63, v63
	v_fma_f32 v139, v12, v139, v50
	v_fmac_f32_e32 v139, v30, v131
	v_fmac_f32_e32 v139, v38, v111
	v_add_f32_e32 v63, 1.0, v63
	v_rcp_f32_e32 v63, v63
	v_fmac_f32_e32 v139, v46, v128
	v_fma_f32 v132, v13, v132, v51
	v_fmac_f32_e32 v132, v31, v130
	v_mul_f32_e32 v62, v62, v63
	v_fma_f32 v63, v23, v142, v55
	v_fmac_f32_e32 v63, v27, v135
	v_fmac_f32_e32 v63, v35, v77
	v_fmac_f32_e32 v63, v43, v125
	v_mul_f32_e32 v142, 0xbfb8aa3b, v63
	v_exp_f32_e32 v142, v142
	v_fmac_f32_e32 v132, v39, v79
	v_fmac_f32_e32 v132, v47, v129
	v_add_u32_e32 v146, s17, v102
	v_add_f32_e32 v142, 1.0, v142
	v_rcp_f32_e32 v142, v142
	v_cmp_gt_i32_e32 vcc, s15, v146
	v_cvt_pk_bf16_f32 v60, v60, s0
	v_cvt_pk_bf16_f32 v61, v61, s0
	v_mul_f32_e32 v63, v63, v142
	v_mul_f32_e32 v142, 0xbfb8aa3b, v141
	v_exp_f32_e32 v142, v142
	v_cndmask_b32_e32 v60, 0, v60, vcc
	v_cndmask_b32_e32 v61, 0, v61, vcc
	v_cvt_pk_bf16_f32 v62, v62, s0
	v_add_f32_e32 v142, 1.0, v142
	v_rcp_f32_e32 v142, v142
	v_cndmask_b32_e32 v62, 0, v62, vcc
	v_cvt_pk_bf16_f32 v63, v63, s0
	v_cndmask_b32_e32 v63, 0, v63, vcc
	v_mul_f32_e32 v141, v141, v142
	v_mul_f32_e32 v142, 0xbfb8aa3b, v140
	v_exp_f32_e32 v142, v142
	v_cvt_pk_bf16_f32 v141, v141, s0
	v_cndmask_b32_e32 v141, 0, v141, vcc
	s_add_i32 s17, s17, 1
	v_add_f32_e32 v142, 1.0, v142
	v_rcp_f32_e32 v142, v142
	s_cmp_lg_u32 s17, 16
	v_mov_b32_e32 v145, v138
	v_mov_b32_e32 v144, v137
	v_mul_f32_e32 v140, v140, v142
	v_mul_f32_e32 v142, 0xbfb8aa3b, v139
	v_exp_f32_e32 v142, v142
	v_cvt_pk_bf16_f32 v140, v140, s0
	v_cndmask_b32_e32 v140, 0, v140, vcc
	v_mov_b32_e32 v143, v136
	v_add_f32_e32 v142, 1.0, v142
	v_rcp_f32_e32 v142, v142
	s_nop 0
	v_mul_f32_e32 v139, v139, v142
	v_mul_f32_e32 v142, 0xbfb8aa3b, v132
	v_exp_f32_e32 v142, v142
	v_cvt_pk_bf16_f32 v139, v139, s0
	v_cndmask_b32_e32 v139, 0, v139, vcc
	v_add_f32_e32 v142, 1.0, v142
	v_rcp_f32_e32 v142, v142
	s_nop 0
	v_mul_f32_e32 v132, v132, v142
	v_xor_b32_e32 v142, v146, v80
	v_lshl_add_u32 v142, v142, 1, v81
	ds_write_b16 v142, v60
	v_xor_b32_e32 v60, v146, v82
	v_lshl_add_u32 v60, v60, 1, v83
	ds_write_b16 v60, v61
	v_xor_b32_e32 v60, v146, v104
	v_lshl_add_u32 v60, v60, 1, v112
	ds_write_b16 v60, v62
	v_xor_b32_e32 v60, v146, v113
	v_lshl_add_u32 v60, v60, 1, v114
	ds_write_b16 v60, v63
	v_xor_b32_e32 v60, v146, v115
	v_lshl_add_u32 v60, v60, 1, v116
	ds_write_b16 v60, v141
	v_xor_b32_e32 v60, v146, v117
	v_lshl_add_u32 v60, v60, 1, v118
	ds_write_b16 v60, v140
	v_xor_b32_e32 v60, v146, v119
	v_lshl_add_u32 v60, v60, 1, v120
	ds_write_b16 v60, v139
	v_cvt_pk_bf16_f32 v60, v132, s0
	v_xor_b32_e32 v61, v146, v121
	v_cndmask_b32_e32 v60, 0, v60, vcc
	v_lshl_add_u32 v61, v61, 1, v122
	ds_write_b16 v61, v60
	v_mov_b32_e32 v142, v135
	v_mov_b32_e32 v141, v134
	v_mov_b32_e32 v140, v133
	v_mov_b32_e32 v139, v131
	v_mov_b32_e32 v132, v130
	s_cmp_lt_u32 s17, 13
	s_cbranch_scc1 .Lsa_w3_2
	s_waitcnt vmcnt(0)
	s_cmp_lg_u32 s17, 16
	s_cbranch_scc0 .LBB0_489
	s_branch .Lsa_top_3

; __device__ __forceinline__ void unpack8(const u32x4 w, float* f) { f[0] = bflo(w.x); f[1] = bfhi(w.x); f[2] = bflo(w.y); f[3] = bfhi(w.y); f[4] = bflo(w.z); f[5] = bfhi(w.z); f[6] = bflo(w.w); f[7] = bfhi(w.w); }
; #define SSD_LD(tt) ((live && (tt) >= 0) ? *(const u32x4*)(PJ + (size_t)tok_row(b, (tt)) * PW + C_XBC + xcol) : (u32x4){0u, 0u, 0u, 0u})
; template <bool PASSA> __device__ __forceinline__ void ssd_stage(const Ptrs& P, int l, int b, int ch, int gg, unsigned char* lds, int tid) {
;     ...
;         { const u32x4 h0 = SSD_LD(t0 - 3), h1 = SSD_LD(t0 - 2), h2 = SSD_LD(t0 - 1); unpack8(h0, x0); unpack8(h1, x1); unpack8(h2, x2); }
;         u32x4 n0 = SSD_LD(t0), n1 = SSD_LD(t0 + 1), n2 = SSD_LD(t0 + 2), n3 = SSD_LD(t0 + 3);
; #pragma unroll 1
;         for (int i = 0; i < 16; ++i) {
;             const int li = l0 + i;
;             unpack8(n0, x3); n0 = n1; n1 = n2; n2 = n3; n3 = (i + 4 < 16) ? SSD_LD(t0 + i + 4) : (u32x4){0u, 0u, 0u, 0u};
.Lsa_top_3:
	v_mov_b32_e32 v136, v109
	v_mov_b32_e32 v137, v76
	v_mov_b32_e32 v76, v18
	v_mov_b32_e32 v109, v19
	s_cmp_lt_u32 s17, 12
	v_mov_b32_e32 v18, v16
	v_mov_b32_e32 v19, v16
	v_mov_b32_e32 v138, v105
	v_mov_b32_e32 v105, v17
	s_cselect_b64 s[8:9], -1, 0
	v_mov_b32_e32 v17, v16
	v_mov_b64_e32 v[62:63], v[18:19]
	v_mov_b32_e32 v130, v79
	v_mov_b32_e32 v131, v111
	v_mov_b32_e32 v133, v78
	v_mov_b32_e32 v134, v110
	v_mov_b32_e32 v135, v77
	v_mov_b32_e32 v77, v125
	v_mov_b32_e32 v110, v126
	v_mov_b32_e32 v78, v127
	v_mov_b32_e32 v111, v128
	v_mov_b32_e32 v79, v129
	s_and_b64 s[10:11], s[40:41], s[8:9]
	v_mov_b64_e32 v[60:61], v[16:17]
	s_and_saveexec_b64 s[8:9], s[10:11]
	s_cbranch_execz .Lsa3_484
	v_mov_b32_e32 v18, v16
	v_mov_b32_e32 v19, v16
	v_add_u32_e32 v125, s17, v103
	v_mov_b32_e32 v17, v16
	v_mov_b64_e32 v[62:63], v[18:19]
	v_cmp_lt_i32_e32 vcc, -5, v125
	v_mov_b64_e32 v[60:61], v[16:17]
	s_and_saveexec_b64 s[10:11], vcc
	s_cbranch_execz .Lsa3_483
	v_add_u32_e32 v17, 4, v125
	v_cmp_gt_u32_e32 vcc, 16, v17
	s_nop 1
	v_cndmask_b32_e32 v17, v124, v123, vcc
	v_add_u32_e32 v17, s17, v17
	v_mad_i64_i32 v[18:19], s[18:19], v17, s34, v[86:87]
	v_lshl_add_u64 v[18:19], v[100:101], 1, v[18:19]
	v_add_co_u32_e32 v18, vcc, 0x1000, v18
	s_nop 1
	v_addc_co_u32_e32 v19, vcc, 0, v19, vcc
	global_load_dwordx4 v[60:63], v[18:19], off offset:2560
	s_branch .Lsa3_483

; __device__ __forceinline__ unsigned f2bf(float f) { return pk2(f, 0.f) & 0xffffu; }
; __device__ __forceinline__ float siluf(float x) { return x * __builtin_amdgcn_rcpf(1.0f + __expf(-x)); }
; __device__ __forceinline__ void unpack8(const u32x4 w, float* f) { f[0] = bflo(w.x); f[1] = bfhi(w.x); f[2] = bflo(w.y); f[3] = bfhi(w.y); f[4] = bflo(w.z); f[5] = bfhi(w.z); f[6] = bflo(w.w); f[7] = bfhi(w.w); }
; #define SSD_LD(tt) ((live && (tt) >= 0) ? *(const u32x4*)(PJ + (size_t)tok_row(b, (tt)) * PW + C_XBC + xcol) : (u32x4){0u, 0u, 0u, 0u})
; template <bool PASSA> __device__ __forceinline__ void ssd_stage(const Ptrs& P, int l, int b, int ch, int gg, unsigned char* lds, int tid) {
;     ...
;         for (int i = 0; i < 16; ++i) {
;             const int li = l0 + i;
;             unpack8(n0, x3); n0 = n1; n1 = n2; n2 = n3; n3 = (i + 4 < 16) ? SSD_LD(t0 + i + 4) : (u32x4){0u, 0u, 0u, 0u};
;             float o[8];
; #pragma unroll
;             for (int e = 0; e < 8; ++e) { float v = bias[e] + wgt[0][e] * x0[e] + wgt[1][e] * x1[e] + wgt[2][e] * x2[e] + wgt[3][e] * x3[e]; v = siluf(v); o[e] = (li < nvalid) ? v : 0.f;
;                 x0[e] = x1[e]; x1[e] = x2[e]; x2[e] = x3[e]; }
;             if (kind == 0) {
; #pragma unroll
;                 for (int e = 0; e < 8; ++e) Xt[sdz(i0 + e, li)] = (bf16_t)f2bf(o[e]);
;             } else if (kind == 1) {
;                 if (PASSA) {
; #pragma unroll
;                     for (int e = 0; e < 8; ++e) Bs[sdz(i0 + e, li)] = (bf16_t)f2bf(o[e]);
.Lsa3_484:
	s_or_b64 exec, exec, s[8:9]
	v_lshlrev_b32_e32 v17, 16, v64
	v_and_b32_e32 v18, 0xffff0000, v64
	v_fma_f32 v64, v20, v145, v52
	v_fmac_f32_e32 v64, v24, v138
	v_fmac_f32_e32 v64, v32, v105
	v_fmac_f32_e32 v64, v40, v17
	v_lshlrev_b32_e32 v19, 16, v65
	v_and_b32_e32 v125, 0xffff0000, v65
	v_mul_f32_e32 v65, 0xbfb8aa3b, v64
	v_exp_f32_e32 v65, v65
	v_lshlrev_b32_e32 v126, 16, v66
	v_and_b32_e32 v127, 0xffff0000, v66
	v_lshlrev_b32_e32 v128, 16, v67
	v_add_f32_e32 v65, 1.0, v65
	v_rcp_f32_e32 v65, v65
	v_and_b32_e32 v129, 0xffff0000, v67
	v_fma_f32 v141, v10, v141, v48
	v_fmac_f32_e32 v141, v28, v134
	v_mul_f32_e32 v64, v64, v65
	v_fma_f32 v65, v21, v144, v53
	v_fmac_f32_e32 v65, v25, v137
	v_fmac_f32_e32 v65, v33, v76
	v_fmac_f32_e32 v65, v41, v18
	v_mul_f32_e32 v66, 0xbfb8aa3b, v65
	v_exp_f32_e32 v66, v66
	v_fmac_f32_e32 v141, v36, v110
	v_fmac_f32_e32 v141, v44, v126
	v_fma_f32 v140, v11, v140, v49
	v_add_f32_e32 v66, 1.0, v66
	v_rcp_f32_e32 v66, v66
	v_fmac_f32_e32 v140, v29, v133
	v_fmac_f32_e32 v140, v37, v78
	v_fmac_f32_e32 v140, v45, v127
	v_mul_f32_e32 v65, v65, v66
	v_fma_f32 v66, v22, v143, v54
	v_fmac_f32_e32 v66, v26, v136
	v_fmac_f32_e32 v66, v34, v109
	v_fmac_f32_e32 v66, v42, v19
	v_mul_f32_e32 v67, 0xbfb8aa3b, v66
	v_exp_f32_e32 v67, v67
	v_fma_f32 v139, v12, v139, v50
	v_fmac_f32_e32 v139, v30, v131
	v_fmac_f32_e32 v139, v38, v111
	v_add_f32_e32 v67, 1.0, v67
	v_rcp_f32_e32 v67, v67
	v_fmac_f32_e32 v139, v46, v128
	v_fma_f32 v132, v13, v132, v51
	v_fmac_f32_e32 v132, v31, v130
	v_mul_f32_e32 v66, v66, v67
	v_fma_f32 v67, v23, v142, v55
	v_fmac_f32_e32 v67, v27, v135
	v_fmac_f32_e32 v67, v35, v77
	v_fmac_f32_e32 v67, v43, v125
	v_mul_f32_e32 v142, 0xbfb8aa3b, v67
	v_exp_f32_e32 v142, v142
	v_fmac_f32_e32 v132, v39, v79
	v_fmac_f32_e32 v132, v47, v129
	v_add_u32_e32 v146, s17, v102
	v_add_f32_e32 v142, 1.0, v142
	v_rcp_f32_e32 v142, v142
	v_cmp_gt_i32_e32 vcc, s15, v146
	v_cvt_pk_bf16_f32 v64, v64, s0
	v_cvt_pk_bf16_f32 v65, v65, s0
	v_mul_f32_e32 v67, v67, v142
	v_mul_f32_e32 v142, 0xbfb8aa3b, v141
	v_exp_f32_e32 v142, v142
	v_cndmask_b32_e32 v64, 0, v64, vcc
	v_cndmask_b32_e32 v65, 0, v65, vcc
	v_cvt_pk_bf16_f32 v66, v66, s0
	v_add_f32_e32 v142, 1.0, v142
	v_rcp_f32_e32 v142, v142
	v_cndmask_b32_e32 v66, 0, v66, vcc
	v_cvt_pk_bf16_f32 v67, v67, s0
	v_cndmask_b32_e32 v67, 0, v67, vcc
	v_mul_f32_e32 v141, v141, v142
	v_mul_f32_e32 v142, 0xbfb8aa3b, v140
	v_exp_f32_e32 v142, v142
	v_cvt_pk_bf16_f32 v141, v141, s0
	v_cndmask_b32_e32 v141, 0, v141, vcc
	s_add_i32 s17, s17, 1
	v_add_f32_e32 v142, 1.0, v142
	v_rcp_f32_e32 v142, v142
	s_cmp_lg_u32 s17, 16
	v_mov_b32_e32 v145, v138
	v_mov_b32_e32 v144, v137
	v_mul_f32_e32 v140, v140, v142
	v_mul_f32_e32 v142, 0xbfb8aa3b, v139
	v_exp_f32_e32 v142, v142
	v_cvt_pk_bf16_f32 v140, v140, s0
	v_cndmask_b32_e32 v140, 0, v140, vcc
	v_mov_b32_e32 v143, v136
	v_add_f32_e32 v142, 1.0, v142
	v_rcp_f32_e32 v142, v142
	s_nop 0
	v_mul_f32_e32 v139, v139, v142
	v_mul_f32_e32 v142, 0xbfb8aa3b, v132
	v_exp_f32_e32 v142, v142
	v_cvt_pk_bf16_f32 v139, v139, s0
	v_cndmask_b32_e32 v139, 0, v139, vcc
	v_add_f32_e32 v142, 1.0, v142
	v_rcp_f32_e32 v142, v142
	s_nop 0
	v_mul_f32_e32 v132, v132, v142
	v_xor_b32_e32 v142, v146, v80
	v_lshl_add_u32 v142, v142, 1, v81
	ds_write_b16 v142, v64
	v_xor_b32_e32 v64, v146, v82
	v_lshl_add_u32 v64, v64, 1, v83
	ds_write_b16 v64, v65
	v_xor_b32_e32 v64, v146, v104
	v_lshl_add_u32 v64, v64, 1, v112
	ds_write_b16 v64, v66
	v_xor_b32_e32 v64, v146, v113
	v_lshl_add_u32 v64, v64, 1, v114
	ds_write_b16 v64, v67
	v_xor_b32_e32 v64, v146, v115
	v_lshl_add_u32 v64, v64, 1, v116
	ds_write_b16 v64, v141
	v_xor_b32_e32 v64, v146, v117
	v_lshl_add_u32 v64, v64, 1, v118
	ds_write_b16 v64, v140
	v_xor_b32_e32 v64, v146, v119
	v_lshl_add_u32 v64, v64, 1, v120
	ds_write_b16 v64, v139
	v_cvt_pk_bf16_f32 v64, v132, s0
	v_xor_b32_e32 v65, v146, v121
	v_cndmask_b32_e32 v64, 0, v64, vcc
	v_lshl_add_u32 v65, v65, 1, v122
	ds_write_b16 v65, v64
	v_mov_b32_e32 v142, v135
	v_mov_b32_e32 v141, v134
	v_mov_b32_e32 v140, v133
	v_mov_b32_e32 v139, v131
	v_mov_b32_e32 v132, v130
	s_cmp_lt_u32 s17, 13
	s_cbranch_scc1 .Lsa_w3_3
	s_waitcnt vmcnt(0)
	s_cmp_lg_u32 s17, 16
	s_cbranch_scc0 .LBB0_489
	s_branch .Lsa_top_4

; __device__ __forceinline__ void unpack8(const u32x4 w, float* f) { f[0] = bflo(w.x); f[1] = bfhi(w.x); f[2] = bflo(w.y); f[3] = bfhi(w.y); f[4] = bflo(w.z); f[5] = bfhi(w.z); f[6] = bflo(w.w); f[7] = bfhi(w.w); }
; #define SSD_LD(tt) ((live && (tt) >= 0) ? *(const u32x4*)(PJ + (size_t)tok_row(b, (tt)) * PW + C_XBC + xcol) : (u32x4){0u, 0u, 0u, 0u})
; template <bool PASSA> __device__ __forceinline__ void ssd_stage(const Ptrs& P, int l, int b, int ch, int gg, unsigned char* lds, int tid) {
;     ...
;         { const u32x4 h0 = SSD_LD(t0 - 3), h1 = SSD_LD(t0 - 2), h2 = SSD_LD(t0 - 1); unpack8(h0, x0); unpack8(h1, x1); unpack8(h2, x2); }
;         u32x4 n0 = SSD_LD(t0), n1 = SSD_LD(t0 + 1), n2 = SSD_LD(t0 + 2), n3 = SSD_LD(t0 + 3);
; #pragma unroll 1
;         for (int i = 0; i < 16; ++i) {
;             const int li = l0 + i;
;             unpack8(n0, x3); n0 = n1; n1 = n2; n2 = n3; n3 = (i + 4 < 16) ? SSD_LD(t0 + i + 4) : (u32x4){0u, 0u, 0u, 0u};
.Lsa_top_4:
	v_mov_b32_e32 v136, v109
	v_mov_b32_e32 v137, v76
	v_mov_b32_e32 v76, v18
	v_mov_b32_e32 v109, v19
	s_cmp_lt_u32 s17, 12
	v_mov_b32_e32 v18, v16
	v_mov_b32_e32 v19, v16
	v_mov_b32_e32 v138, v105
	v_mov_b32_e32 v105, v17
	s_cselect_b64 s[8:9], -1, 0
	v_mov_b32_e32 v17, v16
	v_mov_b64_e32 v[66:67], v[18:19]
	v_mov_b32_e32 v130, v79
	v_mov_b32_e32 v131, v111
	v_mov_b32_e32 v133, v78
	v_mov_b32_e32 v134, v110
	v_mov_b32_e32 v135, v77
	v_mov_b32_e32 v77, v125
	v_mov_b32_e32 v110, v126
	v_mov_b32_e32 v78, v127
	v_mov_b32_e32 v111, v128
	v_mov_b32_e32 v79, v129
	s_and_b64 s[10:11], s[40:41], s[8:9]
	v_mov_b64_e32 v[64:65], v[16:17]
	s_and_saveexec_b64 s[8:9], s[10:11]
	s_cbranch_execz .Lsa4_484
	v_mov_b32_e32 v18, v16
	v_mov_b32_e32 v19, v16
	v_add_u32_e32 v125, s17, v103
	v_mov_b32_e32 v17, v16
	v_mov_b64_e32 v[66:67], v[18:19]
	v_cmp_lt_i32_e32 vcc, -5, v125
	v_mov_b64_e32 v[64:65], v[16:17]
	s_and_saveexec_b64 s[10:11], vcc
	s_cbranch_execz .Lsa4_483
	v_add_u32_e32 v17, 4, v125
	v_cmp_gt_u32_e32 vcc, 16, v17
	s_nop 1
	v_cndmask_b32_e32 v17, v124, v123, vcc
	v_add_u32_e32 v17, s17, v17
	v_mad_i64_i32 v[18:19], s[18:19], v17, s34, v[86:87]
	v_lshl_add_u64 v[18:19], v[100:101], 1, v[18:19]
	v_add_co_u32_e32 v18, vcc, 0x1000, v18
	s_nop 1
	v_addc_co_u32_e32 v19, vcc, 0, v19, vcc
	global_load_dwordx4 v[64:67], v[18:19], off offset:2560
	s_branch .Lsa4_483

; __device__ __forceinline__ unsigned f2bf(float f) { return pk2(f, 0.f) & 0xffffu; }
; __device__ __forceinline__ float siluf(float x) { return x * __builtin_amdgcn_rcpf(1.0f + __expf(-x)); }
; __device__ __forceinline__ void unpack8(const u32x4 w, float* f) { f[0] = bflo(w.x); f[1] = bfhi(w.x); f[2] = bflo(w.y); f[3] = bfhi(w.y); f[4] = bflo(w.z); f[5] = bfhi(w.z); f[6] = bflo(w.w); f[7] = bfhi(w.w); }
; #define SSD_LD(tt) ((live && (tt) >= 0) ? *(const u32x4*)(PJ + (size_t)tok_row(b, (tt)) * PW + C_XBC + xcol) : (u32x4){0u, 0u, 0u, 0u})
; template <bool PASSA> __device__ __forceinline__ void ssd_stage(const Ptrs& P, int l, int b, int ch, int gg, unsigned char* lds, int tid) {
;     ...
;         for (int i = 0; i < 16; ++i) {
;             const int li = l0 + i;
;             unpack8(n0, x3); n0 = n1; n1 = n2; n2 = n3; n3 = (i + 4 < 16) ? SSD_LD(t0 + i + 4) : (u32x4){0u, 0u, 0u, 0u};
;             float o[8];
; #pragma unroll
;             for (int e = 0; e < 8; ++e) { float v = bias[e] + wgt[0][e] * x0[e] + wgt[1][e] * x1[e] + wgt[2][e] * x2[e] + wgt[3][e] * x3[e]; v = siluf(v); o[e] = (li < nvalid) ? v : 0.f;
;                 x0[e] = x1[e]; x1[e] = x2[e]; x2[e] = x3[e]; }
;             if (kind == 0) {
; #pragma unroll
;                 for (int e = 0; e < 8; ++e) Xt[sdz(i0 + e, li)] = (bf16_t)f2bf(o[e]);
;             } else if (kind == 1) {
;                 if (PASSA) {
; #pragma unroll
;                     for (int e = 0; e < 8; ++e) Bs[sdz(i0 + e, li)] = (bf16_t)f2bf(o[e]);
.Lsa4_484:
	s_or_b64 exec, exec, s[8:9]
	v_lshlrev_b32_e32 v17, 16, v68
	v_and_b32_e32 v18, 0xffff0000, v68
	v_fma_f32 v68, v20, v145, v52
	v_fmac_f32_e32 v68, v24, v138
	v_fmac_f32_e32 v68, v32, v105
	v_fmac_f32_e32 v68, v40, v17
	v_lshlrev_b32_e32 v19, 16, v69
	v_and_b32_e32 v125, 0xffff0000, v69
	v_mul_f32_e32 v69, 0xbfb8aa3b, v68
	v_exp_f32_e32 v69, v69
	v_lshlrev_b32_e32 v126, 16, v70
	v_and_b32_e32 v127, 0xffff0000, v70
	v_lshlrev_b32_e32 v128, 16, v71
	v_add_f32_e32 v69, 1.0, v69
	v_rcp_f32_e32 v69, v69
	v_and_b32_e32 v129, 0xffff0000, v71
	v_fma_f32 v141, v10, v141, v48
	v_fmac_f32_e32 v141, v28, v134
	v_mul_f32_e32 v68, v68, v69
	v_fma_f32 v69, v21, v144, v53
	v_fmac_f32_e32 v69, v25, v137
	v_fmac_f32_e32 v69, v33, v76
	v_fmac_f32_e32 v69, v41, v18
	v_mul_f32_e32 v70, 0xbfb8aa3b, v69
	v_exp_f32_e32 v70, v70
	v_fmac_f32_e32 v141, v36, v110
	v_fmac_f32_e32 v141, v44, v126
	v_fma_f32 v140, v11, v140, v49
	v_add_f32_e32 v70, 1.0, v70
	v_rcp_f32_e32 v70, v70
	v_fmac_f32_e32 v140, v29, v133
	v_fmac_f32_e32 v140, v37, v78
	v_fmac_f32_e32 v140, v45, v127
	v_mul_f32_e32 v69, v69, v70
	v_fma_f32 v70, v22, v143, v54
	v_fmac_f32_e32 v70, v26, v136
	v_fmac_f32_e32 v70, v34, v109
	v_fmac_f32_e32 v70, v42, v19
	v_mul_f32_e32 v71, 0xbfb8aa3b, v70
	v_exp_f32_e32 v71, v71
	v_fma_f32 v139, v12, v139, v50
	v_fmac_f32_e32 v139, v30, v131
	v_fmac_f32_e32 v139, v38, v111
	v_add_f32_e32 v71, 1.0, v71
	v_rcp_f32_e32 v71, v71
	v_fmac_f32_e32 v139, v46, v128
	v_fma_f32 v132, v13, v132, v51
	v_fmac_f32_e32 v132, v31, v130
	v_mul_f32_e32 v70, v70, v71
	v_fma_f32 v71, v23, v142, v55
	v_fmac_f32_e32 v71, v27, v135
	v_fmac_f32_e32 v71, v35, v77
	v_fmac_f32_e32 v71, v43, v125
	v_mul_f32_e32 v142, 0xbfb8aa3b, v71
	v_exp_f32_e32 v142, v142
	v_fmac_f32_e32 v132, v39, v79
	v_fmac_f32_e32 v132, v47, v129
	v_add_u32_e32 v146, s17, v102
	v_add_f32_e32 v142, 1.0, v142
	v_rcp_f32_e32 v142, v142
	v_cmp_gt_i32_e32 vcc, s15, v146
	v_cvt_pk_bf16_f32 v68, v68, s0
	v_cvt_pk_bf16_f32 v69, v69, s0
	v_mul_f32_e32 v71, v71, v142
	v_mul_f32_e32 v142, 0xbfb8aa3b, v141
	v_exp_f32_e32 v142, v142
	v_cndmask_b32_e32 v68, 0, v68, vcc
	v_cndmask_b32_e32 v69, 0, v69, vcc
	v_cvt_pk_bf16_f32 v70, v70, s0
	v_add_f32_e32 v142, 1.0, v142
	v_rcp_f32_e32 v142, v142
	v_cndmask_b32_e32 v70, 0, v70, vcc
	v_cvt_pk_bf16_f32 v71, v71, s0
	v_cndmask_b32_e32 v71, 0, v71, vcc
	v_mul_f32_e32 v141, v141, v142
	v_mul_f32_e32 v142, 0xbfb8aa3b, v140
	v_exp_f32_e32 v142, v142
	v_cvt_pk_bf16_f32 v141, v141, s0
	v_cndmask_b32_e32 v141, 0, v141, vcc
	s_add_i32 s17, s17, 1
	v_add_f32_e32 v142, 1.0, v142
	v_rcp_f32_e32 v142, v142
	s_cmp_lg_u32 s17, 16
	v_mov_b32_e32 v145, v138
	v_mov_b32_e32 v144, v137
	v_mul_f32_e32 v140, v140, v142
	v_mul_f32_e32 v142, 0xbfb8aa3b, v139
	v_exp_f32_e32 v142, v142
	v_cvt_pk_bf16_f32 v140, v140, s0
	v_cndmask_b32_e32 v140, 0, v140, vcc
	v_mov_b32_e32 v143, v136
	v_add_f32_e32 v142, 1.0, v142
	v_rcp_f32_e32 v142, v142
	s_nop 0
	v_mul_f32_e32 v139, v139, v142
	v_mul_f32_e32 v142, 0xbfb8aa3b, v132
	v_exp_f32_e32 v142, v142
	v_cvt_pk_bf16_f32 v139, v139, s0
	v_cndmask_b32_e32 v139, 0, v139, vcc
	v_add_f32_e32 v142, 1.0, v142
	v_rcp_f32_e32 v142, v142
	s_nop 0
	v_mul_f32_e32 v132, v132, v142
	v_xor_b32_e32 v142, v146, v80
	v_lshl_add_u32 v142, v142, 1, v81
	ds_write_b16 v142, v68
	v_xor_b32_e32 v68, v146, v82
	v_lshl_add_u32 v68, v68, 1, v83
	ds_write_b16 v68, v69
	v_xor_b32_e32 v68, v146, v104
	v_lshl_add_u32 v68, v68, 1, v112
	ds_write_b16 v68, v70
	v_xor_b32_e32 v68, v146, v113
	v_lshl_add_u32 v68, v68, 1, v114
	ds_write_b16 v68, v71
	v_xor_b32_e32 v68, v146, v115
	v_lshl_add_u32 v68, v68, 1, v116
	ds_write_b16 v68, v141
	v_xor_b32_e32 v68, v146, v117
	v_lshl_add_u32 v68, v68, 1, v118
	ds_write_b16 v68, v140
	v_xor_b32_e32 v68, v146, v119
	v_lshl_add_u32 v68, v68, 1, v120
	ds_write_b16 v68, v139
	v_cvt_pk_bf16_f32 v68, v132, s0
	v_xor_b32_e32 v69, v146, v121
	v_cndmask_b32_e32 v68, 0, v68, vcc
	v_lshl_add_u32 v69, v69, 1, v122
	ds_write_b16 v69, v68
	v_mov_b32_e32 v142, v135
	v_mov_b32_e32 v141, v134
	v_mov_b32_e32 v140, v133
	v_mov_b32_e32 v139, v131
	v_mov_b32_e32 v132, v130
	s_cmp_lt_u32 s17, 13
	s_cbranch_scc1 .Lsa_w3_4
	s_waitcnt vmcnt(0)
	s_cmp_lg_u32 s17, 16
	s_cbranch_scc0 .LBB0_489
	s_branch .Lsa_top_0
.Lsa_w3_4:
	s_waitcnt vmcnt(3)
	s_branch .Lsa_top_0

; __device__ __forceinline__ void unpack8(const u32x4 w, float* f) { f[0] = bflo(w.x); f[1] = bfhi(w.x); f[2] = bflo(w.y); f[3] = bfhi(w.y); f[4] = bflo(w.z); f[5] = bfhi(w.z); f[6] = bflo(w.w); f[7] = bfhi(w.w); }
; #define SSD_LD(tt) ((live && (tt) >= 0) ? *(const u32x4*)(PJ + (size_t)tok_row(b, (tt)) * PW + C_XBC + xcol) : (u32x4){0u, 0u, 0u, 0u})
; template <bool PASSA> __device__ __forceinline__ void ssd_stage(const Ptrs& P, int l, int b, int ch, int gg, unsigned char* lds, int tid) {
;     ...
;         { const u32x4 h0 = SSD_LD(t0 - 3), h1 = SSD_LD(t0 - 2), h2 = SSD_LD(t0 - 1); unpack8(h0, x0); unpack8(h1, x1); unpack8(h2, x2); }
;         u32x4 n0 = SSD_LD(t0), n1 = SSD_LD(t0 + 1), n2 = SSD_LD(t0 + 2), n3 = SSD_LD(t0 + 3);
; #pragma unroll 1
;         for (int i = 0; i < 16; ++i) {
;             const int li = l0 + i;
;             unpack8(n0, x3); n0 = n1; n1 = n2; n2 = n3; n3 = (i + 4 < 16) ? SSD_LD(t0 + i + 4) : (u32x4){0u, 0u, 0u, 0u};
.LBB0_924:
	s_or_b64 exec, exec, s[6:7]
	v_add_u32_e32 v17, 1, v88
	v_and_b32_e32 v111, 0x78, v17
	v_add_u32_e32 v17, 2, v88
	v_and_b32_e32 v113, 0x78, v17
	v_add_u32_e32 v17, 3, v88
	s_lshl_b32 s18, s13, 4
	v_and_b32_e32 v115, 0x78, v17
	v_add_u32_e32 v17, 4, v88
	v_and_b32_e32 v117, 0x78, v17
	v_add_u32_e32 v17, 5, v88
	s_add_i32 s6, s17, s18
	v_and_b32_e32 v119, 0x78, v17
	v_add_u32_e32 v17, 6, v88
	s_add_i32 s6, s6, 0x8004
	s_lshl_b32 s15, s13, 14
	v_and_b32_e32 v121, 0x78, v17
	v_add_u32_e32 v17, 7, v88
	v_add_u32_e32 v125, s6, v107
	s_movk_i32 s6, 0x1100
	s_waitcnt vmcnt(0)
	v_lshlrev_b32_e32 v102, 16, v64
	v_and_b32_e32 v103, 0xffff0000, v64
	v_mad_i32_i24 v110, v88, s26, 0
	v_and_b32_e32 v123, 0x78, v17
	s_add_i32 s17, s17, s15
	v_mul_lo_u32 v17, v106, s6
	v_lshlrev_b32_e32 v64, 1, v88
	v_readlane_b32 s6, v255, 25
	v_lshlrev_b32_e32 v82, 16, v72
	v_and_b32_e32 v83, 0xffff0000, v72
	v_lshlrev_b32_e32 v18, 16, v76
	v_and_b32_e32 v19, 0xffff0000, v76
	v_lshlrev_b32_e32 v100, 16, v65
	v_and_b32_e32 v101, 0xffff0000, v65
	v_lshlrev_b32_e32 v72, 16, v73
	v_and_b32_e32 v73, 0xffff0000, v73
	v_lshlrev_b32_e32 v84, 16, v77
	v_and_b32_e32 v85, 0xffff0000, v77
	v_lshlrev_b32_e32 v98, 16, v66
	v_and_b32_e32 v99, 0xffff0000, v66
	v_lshlrev_b32_e32 v76, 16, v74
	v_and_b32_e32 v77, 0xffff0000, v74
	v_lshlrev_b32_e32 v86, 16, v78
	v_and_b32_e32 v87, 0xffff0000, v78
	v_lshlrev_b32_e32 v96, 16, v67
	v_and_b32_e32 v97, 0xffff0000, v67
	v_lshlrev_b32_e32 v74, 16, v75
	v_and_b32_e32 v75, 0xffff0000, v75
	v_lshlrev_b32_e32 v78, 16, v79
	v_and_b32_e32 v79, 0xffff0000, v79
	v_and_b32_e32 v109, 0x78, v88
	v_add_u32_e32 v112, 0x110, v110
	v_add_u32_e32 v114, 0x220, v110
	v_add_u32_e32 v116, 0x330, v110
	v_add_u32_e32 v118, 0x440, v110
	v_add_u32_e32 v120, 0x550, v110
	v_add_u32_e32 v122, 0x660, v110
	v_add_u32_e32 v124, 0x770, v110
	v_add3_u32 v126, s17, -12, v107
	v_add3_u32 v127, v17, v64, s6
	s_mov_b32 s17, 0
	s_branch .Lsb_top_0
.Lsb_top_0:
	v_mov_b64_e32 v[88:89], v[82:83]
	v_mov_b64_e32 v[82:83], v[18:19]
	s_cmp_lt_u32 s17, 12
	v_mov_b32_e32 v18, v16
	v_mov_b32_e32 v19, v16
	s_cselect_b64 s[6:7], -1, 0
	v_mov_b32_e32 v17, v16
	v_mov_b64_e32 v[66:67], v[18:19]
	v_mov_b64_e32 v[90:91], v[72:73]
	v_mov_b64_e32 v[72:73], v[84:85]
	v_mov_b64_e32 v[92:93], v[76:77]
	v_mov_b64_e32 v[76:77], v[86:87]
	v_mov_b64_e32 v[94:95], v[74:75]
	v_mov_b64_e32 v[74:75], v[78:79]
	s_and_b64 s[8:9], s[44:45], s[6:7]
	v_mov_b64_e32 v[64:65], v[16:17]
	s_and_saveexec_b64 s[6:7], s[8:9]
	s_cbranch_execz .Lsb0_930
	v_mov_b32_e32 v18, v16
	v_mov_b32_e32 v19, v16
	v_add_u32_e32 v78, s17, v108
	v_mov_b32_e32 v17, v16
	v_mov_b64_e32 v[66:67], v[18:19]
	v_cmp_lt_i32_e32 vcc, -5, v78
	v_mov_b64_e32 v[64:65], v[16:17]
	s_and_saveexec_b64 s[8:9], vcc
	s_cbranch_execz .Lsb0_929
	v_add_u32_e32 v17, 4, v78
	v_cmp_gt_u32_e32 vcc, 16, v17
	s_nop 1
	v_cndmask_b32_e32 v17, v126, v125, vcc
	v_add_u32_e32 v17, s17, v17
	v_mad_i64_i32 v[18:19], s[20:21], v17, s34, v[160:161]
	v_lshl_add_u64 v[18:19], v[80:81], 1, v[18:19]
	v_add_co_u32_e32 v18, vcc, 0x1000, v18
	s_nop 1
	v_addc_co_u32_e32 v19, vcc, 0, v19, vcc
	global_load_dwordx4 v[64:67], v[18:19], off offset:2560

; __device__ __forceinline__ float siluf(float x) { return x * __builtin_amdgcn_rcpf(1.0f + __expf(-x)); }
; __device__ __forceinline__ void unpack8(const u32x4 w, float* f) { f[0] = bflo(w.x); f[1] = bfhi(w.x); f[2] = bflo(w.y); f[3] = bfhi(w.y); f[4] = bflo(w.z); f[5] = bfhi(w.z); f[6] = bflo(w.w); f[7] = bfhi(w.w); }
; #define SSD_LD(tt) ((live && (tt) >= 0) ? *(const u32x4*)(PJ + (size_t)tok_row(b, (tt)) * PW + C_XBC + xcol) : (u32x4){0u, 0u, 0u, 0u})
; template <bool PASSA> __device__ __forceinline__ void ssd_stage(const Ptrs& P, int l, int b, int ch, int gg, unsigned char* lds, int tid) {
;     ...
;         for (int i = 0; i < 16; ++i) {
;             const int li = l0 + i;
;             unpack8(n0, x3); n0 = n1; n1 = n2; n2 = n3; n3 = (i + 4 < 16) ? SSD_LD(t0 + i + 4) : (u32x4){0u, 0u, 0u, 0u};
;             float o[8];
; #pragma unroll
;             for (int e = 0; e < 8; ++e) { float v = bias[e] + wgt[0][e] * x0[e] + wgt[1][e] * x1[e] + wgt[2][e] * x2[e] + wgt[3][e] * x3[e]; v = siluf(v); o[e] = (li < nvalid) ? v : 0.f;
;                 x0[e] = x1[e]; x1[e] = x2[e]; x2[e] = x3[e]; }
.Lsb_bot_0:
	s_or_b64 exec, exec, s[6:7]
	s_add_i32 s17, s17, 1
	v_add_u32_e32 v127, 0x110, v127
	v_mov_b64_e32 v[96:97], v[94:95]
	v_mov_b64_e32 v[98:99], v[92:93]
	v_mov_b64_e32 v[100:101], v[90:91]
	v_mov_b64_e32 v[102:103], v[88:89]
	s_cmp_lt_u32 s17, 13
	s_cbranch_scc1 .Lsb_w3_0
	s_waitcnt vmcnt(0)
	s_cmp_eq_u32 s17, 16
	s_cbranch_scc1 .LBB0_938
	s_branch .Lsb_top_1

; __device__ __forceinline__ void unpack8(const u32x4 w, float* f) { f[0] = bflo(w.x); f[1] = bfhi(w.x); f[2] = bflo(w.y); f[3] = bfhi(w.y); f[4] = bflo(w.z); f[5] = bfhi(w.z); f[6] = bflo(w.w); f[7] = bfhi(w.w); }
; #define SSD_LD(tt) ((live && (tt) >= 0) ? *(const u32x4*)(PJ + (size_t)tok_row(b, (tt)) * PW + C_XBC + xcol) : (u32x4){0u, 0u, 0u, 0u})
; template <bool PASSA> __device__ __forceinline__ void ssd_stage(const Ptrs& P, int l, int b, int ch, int gg, unsigned char* lds, int tid) {
;     ...
;         { const u32x4 h0 = SSD_LD(t0 - 3), h1 = SSD_LD(t0 - 2), h2 = SSD_LD(t0 - 1); unpack8(h0, x0); unpack8(h1, x1); unpack8(h2, x2); }
;         u32x4 n0 = SSD_LD(t0), n1 = SSD_LD(t0 + 1), n2 = SSD_LD(t0 + 2), n3 = SSD_LD(t0 + 3);
; #pragma unroll 1
;         for (int i = 0; i < 16; ++i) {
;             const int li = l0 + i;
;             unpack8(n0, x3); n0 = n1; n1 = n2; n2 = n3; n3 = (i + 4 < 16) ? SSD_LD(t0 + i + 4) : (u32x4){0u, 0u, 0u, 0u};
.Lsb_top_1:
	v_mov_b64_e32 v[88:89], v[82:83]
	v_mov_b64_e32 v[82:83], v[18:19]
	s_cmp_lt_u32 s17, 12
	v_mov_b32_e32 v18, v16
	v_mov_b32_e32 v19, v16
	s_cselect_b64 s[6:7], -1, 0
	v_mov_b32_e32 v17, v16
	v_mov_b64_e32 v[70:71], v[18:19]
	v_mov_b64_e32 v[90:91], v[72:73]
	v_mov_b64_e32 v[72:73], v[84:85]
	v_mov_b64_e32 v[92:93], v[76:77]
	v_mov_b64_e32 v[76:77], v[86:87]
	v_mov_b64_e32 v[94:95], v[74:75]
	v_mov_b64_e32 v[74:75], v[78:79]
	s_and_b64 s[8:9], s[44:45], s[6:7]
	v_mov_b64_e32 v[68:69], v[16:17]
	s_and_saveexec_b64 s[6:7], s[8:9]
	s_cbranch_execz .Lsb1_930
	v_mov_b32_e32 v18, v16
	v_mov_b32_e32 v19, v16
	v_add_u32_e32 v78, s17, v108
	v_mov_b32_e32 v17, v16
	v_mov_b64_e32 v[70:71], v[18:19]
	v_cmp_lt_i32_e32 vcc, -5, v78
	v_mov_b64_e32 v[68:69], v[16:17]
	s_and_saveexec_b64 s[8:9], vcc
	s_cbranch_execz .Lsb1_929
	v_add_u32_e32 v17, 4, v78
	v_cmp_gt_u32_e32 vcc, 16, v17
	s_nop 1
	v_cndmask_b32_e32 v17, v126, v125, vcc
	v_add_u32_e32 v17, s17, v17
	v_mad_i64_i32 v[18:19], s[20:21], v17, s34, v[160:161]
	v_lshl_add_u64 v[18:19], v[80:81], 1, v[18:19]
	v_add_co_u32_e32 v18, vcc, 0x1000, v18
	s_nop 1
	v_addc_co_u32_e32 v19, vcc, 0, v19, vcc
	global_load_dwordx4 v[68:71], v[18:19], off offset:2560

; __device__ __forceinline__ unsigned pk2(float lo, float hi) { f32x2_t v = {lo, hi}; bf16x2_t b = __builtin_convertvector(v, bf16x2_t); return __builtin_bit_cast(unsigned, b); }
; __device__ __forceinline__ unsigned f2bf(float f) { return pk2(f, 0.f) & 0xffffu; }
; __device__ __forceinline__ float siluf(float x) { return x * __builtin_amdgcn_rcpf(1.0f + __expf(-x)); }
; __device__ __forceinline__ void unpack8(const u32x4 w, float* f) { f[0] = bflo(w.x); f[1] = bfhi(w.x); f[2] = bflo(w.y); f[3] = bfhi(w.y); f[4] = bflo(w.z); f[5] = bfhi(w.z); f[6] = bflo(w.w); f[7] = bfhi(w.w); }
; #define SSD_LD(tt) ((live && (tt) >= 0) ? *(const u32x4*)(PJ + (size_t)tok_row(b, (tt)) * PW + C_XBC + xcol) : (u32x4){0u, 0u, 0u, 0u})
; template <bool PASSA> __device__ __forceinline__ void ssd_stage(const Ptrs& P, int l, int b, int ch, int gg, unsigned char* lds, int tid) {
;     ...
;             unpack8(n0, x3); n0 = n1; n1 = n2; n2 = n3; n3 = (i + 4 < 16) ? SSD_LD(t0 + i + 4) : (u32x4){0u, 0u, 0u, 0u};
;             float o[8];
; #pragma unroll
;             for (int e = 0; e < 8; ++e) { float v = bias[e] + wgt[0][e] * x0[e] + wgt[1][e] * x1[e] + wgt[2][e] * x2[e] + wgt[3][e] * x3[e]; v = siluf(v); o[e] = (li < nvalid) ? v : 0.f;
;                 x0[e] = x1[e]; x1[e] = x2[e]; x2[e] = x3[e]; }
;             if (kind == 0) {
; #pragma unroll
;                 for (int e = 0; e < 8; ++e) Xt[sdz(i0 + e, li)] = (bf16_t)f2bf(o[e]);
;             } else if (kind == 1) {
;                 if (PASSA) {
; #pragma unroll
;                     for (int e = 0; e < 8; ++e) Bs[sdz(i0 + e, li)] = (bf16_t)f2bf(o[e]);
;                 } else { u32x4 wv; wv.x = pk2(o[0], o[1]); wv.y = pk2(o[2], o[3]); wv.z = pk2(o[4], o[5]); wv.w = pk2(o[6], o[7]); *(u32x4*)(Bs + li * 136 + i0) = wv; }
;             } else { u32x4 wv; wv.x = pk2(o[0], o[1]); wv.y = pk2(o[2], o[3]); wv.z = pk2(o[4], o[5]); wv.w = pk2(o[6], o[7]); *(u32x4*)(Cs + li * 136 + i0) = wv; }
.Lsb1_930:
	s_or_b64 exec, exec, s[6:7]
	v_lshlrev_b32_e32 v18, 16, v52
	v_and_b32_e32 v19, 0xffff0000, v52
	v_lshlrev_b32_e32 v84, 16, v53
	v_and_b32_e32 v85, 0xffff0000, v53
	v_pk_fma_f32 v[52:53], v[12:13], v[102:103], v[48:49]
	v_lshlrev_b32_e32 v86, 16, v54
	v_pk_fma_f32 v[52:53], v[20:21], v[88:89], v[52:53]
	v_and_b32_e32 v87, 0xffff0000, v54
	v_pk_fma_f32 v[52:53], v[28:29], v[82:83], v[52:53]
	v_lshlrev_b32_e32 v78, 16, v55
	v_pk_fma_f32 v[52:53], v[36:37], v[18:19], v[52:53]
	v_and_b32_e32 v79, 0xffff0000, v55
	v_mul_f32_e32 v54, 0xbfb8aa3b, v52
	v_mul_f32_e32 v55, 0xbfb8aa3b, v53
	v_exp_f32_e32 v54, v54
	v_exp_f32_e32 v55, v55
	v_add_u32_e32 v17, s17, v107
	v_cmp_gt_i32_e32 vcc, s14, v17
	v_add_f32_e32 v54, 1.0, v54
	v_add_f32_e32 v55, 1.0, v55
	v_rcp_f32_e32 v54, v54
	v_rcp_f32_e32 v55, v55
	v_pk_fma_f32 v[98:99], v[8:9], v[98:99], v[44:45]
	v_pk_fma_f32 v[96:97], v[10:11], v[96:97], v[46:47]
	v_pk_fma_f32 v[98:99], v[24:25], v[92:93], v[98:99]
	v_pk_mul_f32 v[54:55], v[52:53], v[54:55]
	v_pk_fma_f32 v[98:99], v[32:33], v[76:77], v[98:99]
	v_cndmask_b32_e32 v52, 0, v55, vcc
	v_cndmask_b32_e32 v53, 0, v54, vcc
	v_pk_fma_f32 v[54:55], v[14:15], v[100:101], v[50:51]
	v_pk_fma_f32 v[98:99], v[40:41], v[86:87], v[98:99]
	v_pk_fma_f32 v[54:55], v[22:23], v[90:91], v[54:55]
	v_pk_fma_f32 v[96:97], v[26:27], v[94:95], v[96:97]
	v_pk_fma_f32 v[54:55], v[30:31], v[72:73], v[54:55]
	v_pk_fma_f32 v[96:97], v[34:35], v[74:75], v[96:97]
	v_pk_fma_f32 v[54:55], v[38:39], v[84:85], v[54:55]
	v_pk_fma_f32 v[96:97], v[42:43], v[78:79], v[96:97]
	v_mul_f32_e32 v100, 0xbfb8aa3b, v54
	v_mul_f32_e32 v101, 0xbfb8aa3b, v55
	v_exp_f32_e32 v100, v100
	v_exp_f32_e32 v101, v101
	v_add_f32_e32 v100, 1.0, v100
	v_add_f32_e32 v101, 1.0, v101
	v_rcp_f32_e32 v100, v100
	v_rcp_f32_e32 v101, v101
	s_nop 0
	v_pk_mul_f32 v[100:101], v[54:55], v[100:101]
	s_nop 0
	v_cndmask_b32_e32 v54, 0, v101, vcc
	v_cndmask_b32_e32 v55, 0, v100, vcc
	v_mul_f32_e32 v100, 0xbfb8aa3b, v98
	v_mul_f32_e32 v101, 0xbfb8aa3b, v99
	v_exp_f32_e32 v100, v100
	v_exp_f32_e32 v101, v101
	v_add_f32_e32 v100, 1.0, v100
	v_add_f32_e32 v101, 1.0, v101
	v_rcp_f32_e32 v100, v100
	v_rcp_f32_e32 v101, v101
	s_nop 0
	v_pk_mul_f32 v[100:101], v[98:99], v[100:101]
	s_nop 0
	v_cndmask_b32_e32 v98, 0, v101, vcc
	v_cndmask_b32_e32 v99, 0, v100, vcc
	v_mul_f32_e32 v100, 0xbfb8aa3b, v96
	v_mul_f32_e32 v101, 0xbfb8aa3b, v97
	v_exp_f32_e32 v100, v100
	v_exp_f32_e32 v101, v101
	v_add_f32_e32 v100, 1.0, v100
	v_add_f32_e32 v101, 1.0, v101
	v_rcp_f32_e32 v100, v100
	v_rcp_f32_e32 v101, v101
	s_nop 0
	v_pk_mul_f32 v[100:101], v[96:97], v[100:101]
	s_nop 0
	v_cndmask_b32_e32 v96, 0, v101, vcc
	v_cndmask_b32_e32 v97, 0, v100, vcc
	s_and_saveexec_b64 s[6:7], s[42:43]
	s_xor_b64 s[6:7], exec, s[6:7]
	s_cbranch_execz .Lsb1_936
	v_cvt_pk_bf16_f32 v52, v53, v52
	v_cvt_pk_bf16_f32 v53, v55, v54
	v_cvt_pk_bf16_f32 v54, v99, v98
	v_cvt_pk_bf16_f32 v55, v97, v96
	s_and_saveexec_b64 s[8:9], s[4:5]
	s_xor_b64 s[8:9], exec, s[8:9]
	ds_write_b128 v127, v[52:55] offset:34816
	s_andn2_saveexec_b64 s[8:9], s[8:9]
	ds_write_b128 v127, v[52:55]
	s_or_b64 exec, exec, s[8:9]
.Lsb1_936:
	s_andn2_saveexec_b64 s[6:7], s[6:7]
	s_cbranch_execz .Lsb_bot_1
	v_xor_b32_e32 v100, v17, v109
	v_cvt_pk_bf16_f32 v53, v53, s0
	v_lshl_add_u32 v100, v100, 1, v110
	ds_write_b16 v100, v53
	v_xor_b32_e32 v53, v17, v111
	v_cvt_pk_bf16_f32 v52, v52, s0
	v_lshl_add_u32 v53, v53, 1, v112
	ds_write_b16 v53, v52
	v_xor_b32_e32 v53, v17, v113
	v_cvt_pk_bf16_f32 v52, v55, s0
	v_lshl_add_u32 v53, v53, 1, v114
	ds_write_b16 v53, v52
	v_xor_b32_e32 v53, v17, v115
	v_cvt_pk_bf16_f32 v52, v54, s0
	v_lshl_add_u32 v53, v53, 1, v116
	ds_write_b16 v53, v52
	v_xor_b32_e32 v53, v17, v117
	v_cvt_pk_bf16_f32 v52, v99, s0
	v_lshl_add_u32 v53, v53, 1, v118
	ds_write_b16 v53, v52
	v_xor_b32_e32 v53, v17, v119
	v_cvt_pk_bf16_f32 v52, v98, s0
	v_lshl_add_u32 v53, v53, 1, v120
	ds_write_b16 v53, v52
	v_xor_b32_e32 v53, v17, v121
	v_cvt_pk_bf16_f32 v52, v97, s0
	v_lshl_add_u32 v53, v53, 1, v122
	v_xor_b32_e32 v17, v17, v123
	ds_write_b16 v53, v52
	v_cvt_pk_bf16_f32 v52, v96, s0
	v_lshl_add_u32 v17, v17, 1, v124
	ds_write_b16 v17, v52

; __device__ __forceinline__ void unpack8(const u32x4 w, float* f) { f[0] = bflo(w.x); f[1] = bfhi(w.x); f[2] = bflo(w.y); f[3] = bfhi(w.y); f[4] = bflo(w.z); f[5] = bfhi(w.z); f[6] = bflo(w.w); f[7] = bfhi(w.w); }
; #define SSD_LD(tt) ((live && (tt) >= 0) ? *(const u32x4*)(PJ + (size_t)tok_row(b, (tt)) * PW + C_XBC + xcol) : (u32x4){0u, 0u, 0u, 0u})
; template <bool PASSA> __device__ __forceinline__ void ssd_stage(const Ptrs& P, int l, int b, int ch, int gg, unsigned char* lds, int tid) {
;     ...
;         { const u32x4 h0 = SSD_LD(t0 - 3), h1 = SSD_LD(t0 - 2), h2 = SSD_LD(t0 - 1); unpack8(h0, x0); unpack8(h1, x1); unpack8(h2, x2); }
;         u32x4 n0 = SSD_LD(t0), n1 = SSD_LD(t0 + 1), n2 = SSD_LD(t0 + 2), n3 = SSD_LD(t0 + 3);
; #pragma unroll 1
;         for (int i = 0; i < 16; ++i) {
;             const int li = l0 + i;
;             unpack8(n0, x3); n0 = n1; n1 = n2; n2 = n3; n3 = (i + 4 < 16) ? SSD_LD(t0 + i + 4) : (u32x4){0u, 0u, 0u, 0u};
.Lsb_top_2:
	v_mov_b64_e32 v[88:89], v[82:83]
	v_mov_b64_e32 v[82:83], v[18:19]
	s_cmp_lt_u32 s17, 12
	v_mov_b32_e32 v18, v16
	v_mov_b32_e32 v19, v16
	s_cselect_b64 s[6:7], -1, 0
	v_mov_b32_e32 v17, v16
	v_mov_b64_e32 v[54:55], v[18:19]
	v_mov_b64_e32 v[90:91], v[72:73]
	v_mov_b64_e32 v[72:73], v[84:85]
	v_mov_b64_e32 v[92:93], v[76:77]
	v_mov_b64_e32 v[76:77], v[86:87]
	v_mov_b64_e32 v[94:95], v[74:75]
	v_mov_b64_e32 v[74:75], v[78:79]
	s_and_b64 s[8:9], s[44:45], s[6:7]
	v_mov_b64_e32 v[52:53], v[16:17]
	s_and_saveexec_b64 s[6:7], s[8:9]
	s_cbranch_execz .Lsb2_930
	v_mov_b32_e32 v18, v16
	v_mov_b32_e32 v19, v16
	v_add_u32_e32 v78, s17, v108
	v_mov_b32_e32 v17, v16
	v_mov_b64_e32 v[54:55], v[18:19]
	v_cmp_lt_i32_e32 vcc, -5, v78
	v_mov_b64_e32 v[52:53], v[16:17]
	s_and_saveexec_b64 s[8:9], vcc
	s_cbranch_execz .Lsb2_929
	v_add_u32_e32 v17, 4, v78
	v_cmp_gt_u32_e32 vcc, 16, v17
	s_nop 1
	v_cndmask_b32_e32 v17, v126, v125, vcc
	v_add_u32_e32 v17, s17, v17
	v_mad_i64_i32 v[18:19], s[20:21], v17, s34, v[160:161]
	v_lshl_add_u64 v[18:19], v[80:81], 1, v[18:19]
	v_add_co_u32_e32 v18, vcc, 0x1000, v18
	s_nop 1
	v_addc_co_u32_e32 v19, vcc, 0, v19, vcc
	global_load_dwordx4 v[52:55], v[18:19], off offset:2560

; __device__ __forceinline__ unsigned pk2(float lo, float hi) { f32x2_t v = {lo, hi}; bf16x2_t b = __builtin_convertvector(v, bf16x2_t); return __builtin_bit_cast(unsigned, b); }
; __device__ __forceinline__ unsigned f2bf(float f) { return pk2(f, 0.f) & 0xffffu; }
; __device__ __forceinline__ float siluf(float x) { return x * __builtin_amdgcn_rcpf(1.0f + __expf(-x)); }
; __device__ __forceinline__ void unpack8(const u32x4 w, float* f) { f[0] = bflo(w.x); f[1] = bfhi(w.x); f[2] = bflo(w.y); f[3] = bfhi(w.y); f[4] = bflo(w.z); f[5] = bfhi(w.z); f[6] = bflo(w.w); f[7] = bfhi(w.w); }
; #define SSD_LD(tt) ((live && (tt) >= 0) ? *(const u32x4*)(PJ + (size_t)tok_row(b, (tt)) * PW + C_XBC + xcol) : (u32x4){0u, 0u, 0u, 0u})
; template <bool PASSA> __device__ __forceinline__ void ssd_stage(const Ptrs& P, int l, int b, int ch, int gg, unsigned char* lds, int tid) {
;     ...
;             unpack8(n0, x3); n0 = n1; n1 = n2; n2 = n3; n3 = (i + 4 < 16) ? SSD_LD(t0 + i + 4) : (u32x4){0u, 0u, 0u, 0u};
;             float o[8];
; #pragma unroll
;             for (int e = 0; e < 8; ++e) { float v = bias[e] + wgt[0][e] * x0[e] + wgt[1][e] * x1[e] + wgt[2][e] * x2[e] + wgt[3][e] * x3[e]; v = siluf(v); o[e] = (li < nvalid) ? v : 0.f;
;                 x0[e] = x1[e]; x1[e] = x2[e]; x2[e] = x3[e]; }
;             if (kind == 0) {
; #pragma unroll
;                 for (int e = 0; e < 8; ++e) Xt[sdz(i0 + e, li)] = (bf16_t)f2bf(o[e]);
;             } else if (kind == 1) {
;                 if (PASSA) {
; #pragma unroll
;                     for (int e = 0; e < 8; ++e) Bs[sdz(i0 + e, li)] = (bf16_t)f2bf(o[e]);
;                 } else { u32x4 wv; wv.x = pk2(o[0], o[1]); wv.y = pk2(o[2], o[3]); wv.z = pk2(o[4], o[5]); wv.w = pk2(o[6], o[7]); *(u32x4*)(Bs + li * 136 + i0) = wv; }
;             } else { u32x4 wv; wv.x = pk2(o[0], o[1]); wv.y = pk2(o[2], o[3]); wv.z = pk2(o[4], o[5]); wv.w = pk2(o[6], o[7]); *(u32x4*)(Cs + li * 136 + i0) = wv; }
.Lsb2_930:
	s_or_b64 exec, exec, s[6:7]
	v_lshlrev_b32_e32 v18, 16, v56
	v_and_b32_e32 v19, 0xffff0000, v56
	v_lshlrev_b32_e32 v84, 16, v57
	v_and_b32_e32 v85, 0xffff0000, v57
	v_pk_fma_f32 v[56:57], v[12:13], v[102:103], v[48:49]
	v_lshlrev_b32_e32 v86, 16, v58
	v_pk_fma_f32 v[56:57], v[20:21], v[88:89], v[56:57]
	v_and_b32_e32 v87, 0xffff0000, v58
	v_pk_fma_f32 v[56:57], v[28:29], v[82:83], v[56:57]
	v_lshlrev_b32_e32 v78, 16, v59
	v_pk_fma_f32 v[56:57], v[36:37], v[18:19], v[56:57]
	v_and_b32_e32 v79, 0xffff0000, v59
	v_mul_f32_e32 v58, 0xbfb8aa3b, v56
	v_mul_f32_e32 v59, 0xbfb8aa3b, v57
	v_exp_f32_e32 v58, v58
	v_exp_f32_e32 v59, v59
	v_add_u32_e32 v17, s17, v107
	v_cmp_gt_i32_e32 vcc, s14, v17
	v_add_f32_e32 v58, 1.0, v58
	v_add_f32_e32 v59, 1.0, v59
	v_rcp_f32_e32 v58, v58
	v_rcp_f32_e32 v59, v59
	v_pk_fma_f32 v[98:99], v[8:9], v[98:99], v[44:45]
	v_pk_fma_f32 v[96:97], v[10:11], v[96:97], v[46:47]
	v_pk_fma_f32 v[98:99], v[24:25], v[92:93], v[98:99]
	v_pk_mul_f32 v[58:59], v[56:57], v[58:59]
	v_pk_fma_f32 v[98:99], v[32:33], v[76:77], v[98:99]
	v_cndmask_b32_e32 v56, 0, v59, vcc
	v_cndmask_b32_e32 v57, 0, v58, vcc
	v_pk_fma_f32 v[58:59], v[14:15], v[100:101], v[50:51]
	v_pk_fma_f32 v[98:99], v[40:41], v[86:87], v[98:99]
	v_pk_fma_f32 v[58:59], v[22:23], v[90:91], v[58:59]
	v_pk_fma_f32 v[96:97], v[26:27], v[94:95], v[96:97]
	v_pk_fma_f32 v[58:59], v[30:31], v[72:73], v[58:59]
	v_pk_fma_f32 v[96:97], v[34:35], v[74:75], v[96:97]
	v_pk_fma_f32 v[58:59], v[38:39], v[84:85], v[58:59]
	v_pk_fma_f32 v[96:97], v[42:43], v[78:79], v[96:97]
	v_mul_f32_e32 v100, 0xbfb8aa3b, v58
	v_mul_f32_e32 v101, 0xbfb8aa3b, v59
	v_exp_f32_e32 v100, v100
	v_exp_f32_e32 v101, v101
	v_add_f32_e32 v100, 1.0, v100
	v_add_f32_e32 v101, 1.0, v101
	v_rcp_f32_e32 v100, v100
	v_rcp_f32_e32 v101, v101
	s_nop 0
	v_pk_mul_f32 v[100:101], v[58:59], v[100:101]
	s_nop 0
	v_cndmask_b32_e32 v58, 0, v101, vcc
	v_cndmask_b32_e32 v59, 0, v100, vcc
	v_mul_f32_e32 v100, 0xbfb8aa3b, v98
	v_mul_f32_e32 v101, 0xbfb8aa3b, v99
	v_exp_f32_e32 v100, v100
	v_exp_f32_e32 v101, v101
	v_add_f32_e32 v100, 1.0, v100
	v_add_f32_e32 v101, 1.0, v101
	v_rcp_f32_e32 v100, v100
	v_rcp_f32_e32 v101, v101
	s_nop 0
	v_pk_mul_f32 v[100:101], v[98:99], v[100:101]
	s_nop 0
	v_cndmask_b32_e32 v98, 0, v101, vcc
	v_cndmask_b32_e32 v99, 0, v100, vcc
	v_mul_f32_e32 v100, 0xbfb8aa3b, v96
	v_mul_f32_e32 v101, 0xbfb8aa3b, v97
	v_exp_f32_e32 v100, v100
	v_exp_f32_e32 v101, v101
	v_add_f32_e32 v100, 1.0, v100
	v_add_f32_e32 v101, 1.0, v101
	v_rcp_f32_e32 v100, v100
	v_rcp_f32_e32 v101, v101
	s_nop 0
	v_pk_mul_f32 v[100:101], v[96:97], v[100:101]
	s_nop 0
	v_cndmask_b32_e32 v96, 0, v101, vcc
	v_cndmask_b32_e32 v97, 0, v100, vcc
	s_and_saveexec_b64 s[6:7], s[42:43]
	s_xor_b64 s[6:7], exec, s[6:7]
	s_cbranch_execz .Lsb2_936
	v_cvt_pk_bf16_f32 v56, v57, v56
	v_cvt_pk_bf16_f32 v57, v59, v58
	v_cvt_pk_bf16_f32 v58, v99, v98
	v_cvt_pk_bf16_f32 v59, v97, v96
	s_and_saveexec_b64 s[8:9], s[4:5]
	s_xor_b64 s[8:9], exec, s[8:9]
	ds_write_b128 v127, v[56:59] offset:34816
	s_andn2_saveexec_b64 s[8:9], s[8:9]
	ds_write_b128 v127, v[56:59]
	s_or_b64 exec, exec, s[8:9]
.Lsb2_936:
	s_andn2_saveexec_b64 s[6:7], s[6:7]
	s_cbranch_execz .Lsb_bot_2
	v_xor_b32_e32 v100, v17, v109
	v_cvt_pk_bf16_f32 v57, v57, s0
	v_lshl_add_u32 v100, v100, 1, v110
	ds_write_b16 v100, v57
	v_xor_b32_e32 v57, v17, v111
	v_cvt_pk_bf16_f32 v56, v56, s0
	v_lshl_add_u32 v57, v57, 1, v112
	ds_write_b16 v57, v56
	v_xor_b32_e32 v57, v17, v113
	v_cvt_pk_bf16_f32 v56, v59, s0
	v_lshl_add_u32 v57, v57, 1, v114
	ds_write_b16 v57, v56
	v_xor_b32_e32 v57, v17, v115
	v_cvt_pk_bf16_f32 v56, v58, s0
	v_lshl_add_u32 v57, v57, 1, v116
	ds_write_b16 v57, v56
	v_xor_b32_e32 v57, v17, v117
	v_cvt_pk_bf16_f32 v56, v99, s0
	v_lshl_add_u32 v57, v57, 1, v118
	ds_write_b16 v57, v56
	v_xor_b32_e32 v57, v17, v119
	v_cvt_pk_bf16_f32 v56, v98, s0
	v_lshl_add_u32 v57, v57, 1, v120
	ds_write_b16 v57, v56
	v_xor_b32_e32 v57, v17, v121
	v_cvt_pk_bf16_f32 v56, v97, s0
	v_lshl_add_u32 v57, v57, 1, v122
	v_xor_b32_e32 v17, v17, v123
	ds_write_b16 v57, v56
	v_cvt_pk_bf16_f32 v56, v96, s0
	v_lshl_add_u32 v17, v17, 1, v124
	ds_write_b16 v17, v56

; __device__ __forceinline__ void unpack8(const u32x4 w, float* f) { f[0] = bflo(w.x); f[1] = bfhi(w.x); f[2] = bflo(w.y); f[3] = bfhi(w.y); f[4] = bflo(w.z); f[5] = bfhi(w.z); f[6] = bflo(w.w); f[7] = bfhi(w.w); }
; #define SSD_LD(tt) ((live && (tt) >= 0) ? *(const u32x4*)(PJ + (size_t)tok_row(b, (tt)) * PW + C_XBC + xcol) : (u32x4){0u, 0u, 0u, 0u})
; template <bool PASSA> __device__ __forceinline__ void ssd_stage(const Ptrs& P, int l, int b, int ch, int gg, unsigned char* lds, int tid) {
;     ...
;         { const u32x4 h0 = SSD_LD(t0 - 3), h1 = SSD_LD(t0 - 2), h2 = SSD_LD(t0 - 1); unpack8(h0, x0); unpack8(h1, x1); unpack8(h2, x2); }
;         u32x4 n0 = SSD_LD(t0), n1 = SSD_LD(t0 + 1), n2 = SSD_LD(t0 + 2), n3 = SSD_LD(t0 + 3);
; #pragma unroll 1
;         for (int i = 0; i < 16; ++i) {
;             const int li = l0 + i;
;             unpack8(n0, x3); n0 = n1; n1 = n2; n2 = n3; n3 = (i + 4 < 16) ? SSD_LD(t0 + i + 4) : (u32x4){0u, 0u, 0u, 0u};
.Lsb_top_3:
	v_mov_b64_e32 v[88:89], v[82:83]
	v_mov_b64_e32 v[82:83], v[18:19]
	s_cmp_lt_u32 s17, 12
	v_mov_b32_e32 v18, v16
	v_mov_b32_e32 v19, v16
	s_cselect_b64 s[6:7], -1, 0
	v_mov_b32_e32 v17, v16
	v_mov_b64_e32 v[58:59], v[18:19]
	v_mov_b64_e32 v[90:91], v[72:73]
	v_mov_b64_e32 v[72:73], v[84:85]
	v_mov_b64_e32 v[92:93], v[76:77]
	v_mov_b64_e32 v[76:77], v[86:87]
	v_mov_b64_e32 v[94:95], v[74:75]
	v_mov_b64_e32 v[74:75], v[78:79]
	s_and_b64 s[8:9], s[44:45], s[6:7]
	v_mov_b64_e32 v[56:57], v[16:17]
	s_and_saveexec_b64 s[6:7], s[8:9]
	s_cbranch_execz .Lsb3_930
	v_mov_b32_e32 v18, v16
	v_mov_b32_e32 v19, v16
	v_add_u32_e32 v78, s17, v108
	v_mov_b32_e32 v17, v16
	v_mov_b64_e32 v[58:59], v[18:19]
	v_cmp_lt_i32_e32 vcc, -5, v78
	v_mov_b64_e32 v[56:57], v[16:17]
	s_and_saveexec_b64 s[8:9], vcc
	s_cbranch_execz .Lsb3_929
	v_add_u32_e32 v17, 4, v78
	v_cmp_gt_u32_e32 vcc, 16, v17
	s_nop 1
	v_cndmask_b32_e32 v17, v126, v125, vcc
	v_add_u32_e32 v17, s17, v17
	v_mad_i64_i32 v[18:19], s[20:21], v17, s34, v[160:161]
	v_lshl_add_u64 v[18:19], v[80:81], 1, v[18:19]
	v_add_co_u32_e32 v18, vcc, 0x1000, v18
	s_nop 1
	v_addc_co_u32_e32 v19, vcc, 0, v19, vcc
	global_load_dwordx4 v[56:59], v[18:19], off offset:2560

; __device__ __forceinline__ unsigned pk2(float lo, float hi) { f32x2_t v = {lo, hi}; bf16x2_t b = __builtin_convertvector(v, bf16x2_t); return __builtin_bit_cast(unsigned, b); }
; __device__ __forceinline__ unsigned f2bf(float f) { return pk2(f, 0.f) & 0xffffu; }
; __device__ __forceinline__ float siluf(float x) { return x * __builtin_amdgcn_rcpf(1.0f + __expf(-x)); }
; __device__ __forceinline__ void unpack8(const u32x4 w, float* f) { f[0] = bflo(w.x); f[1] = bfhi(w.x); f[2] = bflo(w.y); f[3] = bfhi(w.y); f[4] = bflo(w.z); f[5] = bfhi(w.z); f[6] = bflo(w.w); f[7] = bfhi(w.w); }
; #define SSD_LD(tt) ((live && (tt) >= 0) ? *(const u32x4*)(PJ + (size_t)tok_row(b, (tt)) * PW + C_XBC + xcol) : (u32x4){0u, 0u, 0u, 0u})
; template <bool PASSA> __device__ __forceinline__ void ssd_stage(const Ptrs& P, int l, int b, int ch, int gg, unsigned char* lds, int tid) {
;     ...
;             unpack8(n0, x3); n0 = n1; n1 = n2; n2 = n3; n3 = (i + 4 < 16) ? SSD_LD(t0 + i + 4) : (u32x4){0u, 0u, 0u, 0u};
;             float o[8];
; #pragma unroll
;             for (int e = 0; e < 8; ++e) { float v = bias[e] + wgt[0][e] * x0[e] + wgt[1][e] * x1[e] + wgt[2][e] * x2[e] + wgt[3][e] * x3[e]; v = siluf(v); o[e] = (li < nvalid) ? v : 0.f;
;                 x0[e] = x1[e]; x1[e] = x2[e]; x2[e] = x3[e]; }
;             if (kind == 0) {
; #pragma unroll
;                 for (int e = 0; e < 8; ++e) Xt[sdz(i0 + e, li)] = (bf16_t)f2bf(o[e]);
;             } else if (kind == 1) {
;                 if (PASSA) {
; #pragma unroll
;                     for (int e = 0; e < 8; ++e) Bs[sdz(i0 + e, li)] = (bf16_t)f2bf(o[e]);
;                 } else { u32x4 wv; wv.x = pk2(o[0], o[1]); wv.y = pk2(o[2], o[3]); wv.z = pk2(o[4], o[5]); wv.w = pk2(o[6], o[7]); *(u32x4*)(Bs + li * 136 + i0) = wv; }
;             } else { u32x4 wv; wv.x = pk2(o[0], o[1]); wv.y = pk2(o[2], o[3]); wv.z = pk2(o[4], o[5]); wv.w = pk2(o[6], o[7]); *(u32x4*)(Cs + li * 136 + i0) = wv; }
.Lsb3_930:
	s_or_b64 exec, exec, s[6:7]
	v_lshlrev_b32_e32 v18, 16, v60
	v_and_b32_e32 v19, 0xffff0000, v60
	v_lshlrev_b32_e32 v84, 16, v61
	v_and_b32_e32 v85, 0xffff0000, v61
	v_pk_fma_f32 v[60:61], v[12:13], v[102:103], v[48:49]
	v_lshlrev_b32_e32 v86, 16, v62
	v_pk_fma_f32 v[60:61], v[20:21], v[88:89], v[60:61]
	v_and_b32_e32 v87, 0xffff0000, v62
	v_pk_fma_f32 v[60:61], v[28:29], v[82:83], v[60:61]
	v_lshlrev_b32_e32 v78, 16, v63
	v_pk_fma_f32 v[60:61], v[36:37], v[18:19], v[60:61]
	v_and_b32_e32 v79, 0xffff0000, v63
	v_mul_f32_e32 v62, 0xbfb8aa3b, v60
	v_mul_f32_e32 v63, 0xbfb8aa3b, v61
	v_exp_f32_e32 v62, v62
	v_exp_f32_e32 v63, v63
	v_add_u32_e32 v17, s17, v107
	v_cmp_gt_i32_e32 vcc, s14, v17
	v_add_f32_e32 v62, 1.0, v62
	v_add_f32_e32 v63, 1.0, v63
	v_rcp_f32_e32 v62, v62
	v_rcp_f32_e32 v63, v63
	v_pk_fma_f32 v[98:99], v[8:9], v[98:99], v[44:45]
	v_pk_fma_f32 v[96:97], v[10:11], v[96:97], v[46:47]
	v_pk_fma_f32 v[98:99], v[24:25], v[92:93], v[98:99]
	v_pk_mul_f32 v[62:63], v[60:61], v[62:63]
	v_pk_fma_f32 v[98:99], v[32:33], v[76:77], v[98:99]
	v_cndmask_b32_e32 v60, 0, v63, vcc
	v_cndmask_b32_e32 v61, 0, v62, vcc
	v_pk_fma_f32 v[62:63], v[14:15], v[100:101], v[50:51]
	v_pk_fma_f32 v[98:99], v[40:41], v[86:87], v[98:99]
	v_pk_fma_f32 v[62:63], v[22:23], v[90:91], v[62:63]
	v_pk_fma_f32 v[96:97], v[26:27], v[94:95], v[96:97]
	v_pk_fma_f32 v[62:63], v[30:31], v[72:73], v[62:63]
	v_pk_fma_f32 v[96:97], v[34:35], v[74:75], v[96:97]
	v_pk_fma_f32 v[62:63], v[38:39], v[84:85], v[62:63]
	v_pk_fma_f32 v[96:97], v[42:43], v[78:79], v[96:97]
	v_mul_f32_e32 v100, 0xbfb8aa3b, v62
	v_mul_f32_e32 v101, 0xbfb8aa3b, v63
	v_exp_f32_e32 v100, v100
	v_exp_f32_e32 v101, v101
	v_add_f32_e32 v100, 1.0, v100
	v_add_f32_e32 v101, 1.0, v101
	v_rcp_f32_e32 v100, v100
	v_rcp_f32_e32 v101, v101
	s_nop 0
	v_pk_mul_f32 v[100:101], v[62:63], v[100:101]
	s_nop 0
	v_cndmask_b32_e32 v62, 0, v101, vcc
	v_cndmask_b32_e32 v63, 0, v100, vcc
	v_mul_f32_e32 v100, 0xbfb8aa3b, v98
	v_mul_f32_e32 v101, 0xbfb8aa3b, v99
	v_exp_f32_e32 v100, v100
	v_exp_f32_e32 v101, v101
	v_add_f32_e32 v100, 1.0, v100
	v_add_f32_e32 v101, 1.0, v101
	v_rcp_f32_e32 v100, v100
	v_rcp_f32_e32 v101, v101
	s_nop 0
	v_pk_mul_f32 v[100:101], v[98:99], v[100:101]
	s_nop 0
	v_cndmask_b32_e32 v98, 0, v101, vcc
	v_cndmask_b32_e32 v99, 0, v100, vcc
	v_mul_f32_e32 v100, 0xbfb8aa3b, v96
	v_mul_f32_e32 v101, 0xbfb8aa3b, v97
	v_exp_f32_e32 v100, v100
	v_exp_f32_e32 v101, v101
	v_add_f32_e32 v100, 1.0, v100
	v_add_f32_e32 v101, 1.0, v101
	v_rcp_f32_e32 v100, v100
	v_rcp_f32_e32 v101, v101
	s_nop 0
	v_pk_mul_f32 v[100:101], v[96:97], v[100:101]
	s_nop 0
	v_cndmask_b32_e32 v96, 0, v101, vcc
	v_cndmask_b32_e32 v97, 0, v100, vcc
	s_and_saveexec_b64 s[6:7], s[42:43]
	s_xor_b64 s[6:7], exec, s[6:7]
	s_cbranch_execz .Lsb3_936
	v_cvt_pk_bf16_f32 v60, v61, v60
	v_cvt_pk_bf16_f32 v61, v63, v62
	v_cvt_pk_bf16_f32 v62, v99, v98
	v_cvt_pk_bf16_f32 v63, v97, v96
	s_and_saveexec_b64 s[8:9], s[4:5]
	s_xor_b64 s[8:9], exec, s[8:9]
	ds_write_b128 v127, v[60:63] offset:34816
	s_andn2_saveexec_b64 s[8:9], s[8:9]
	ds_write_b128 v127, v[60:63]
	s_or_b64 exec, exec, s[8:9]
.Lsb3_936:
	s_andn2_saveexec_b64 s[6:7], s[6:7]
	s_cbranch_execz .Lsb_bot_3
	v_xor_b32_e32 v100, v17, v109
	v_cvt_pk_bf16_f32 v61, v61, s0
	v_lshl_add_u32 v100, v100, 1, v110
	ds_write_b16 v100, v61
	v_xor_b32_e32 v61, v17, v111
	v_cvt_pk_bf16_f32 v60, v60, s0
	v_lshl_add_u32 v61, v61, 1, v112
	ds_write_b16 v61, v60
	v_xor_b32_e32 v61, v17, v113
	v_cvt_pk_bf16_f32 v60, v63, s0
	v_lshl_add_u32 v61, v61, 1, v114
	ds_write_b16 v61, v60
	v_xor_b32_e32 v61, v17, v115
	v_cvt_pk_bf16_f32 v60, v62, s0
	v_lshl_add_u32 v61, v61, 1, v116
	ds_write_b16 v61, v60
	v_xor_b32_e32 v61, v17, v117
	v_cvt_pk_bf16_f32 v60, v99, s0
	v_lshl_add_u32 v61, v61, 1, v118
	ds_write_b16 v61, v60
	v_xor_b32_e32 v61, v17, v119
	v_cvt_pk_bf16_f32 v60, v98, s0
	v_lshl_add_u32 v61, v61, 1, v120
	ds_write_b16 v61, v60
	v_xor_b32_e32 v61, v17, v121
	v_cvt_pk_bf16_f32 v60, v97, s0
	v_lshl_add_u32 v61, v61, 1, v122
	v_xor_b32_e32 v17, v17, v123
	ds_write_b16 v61, v60
	v_cvt_pk_bf16_f32 v60, v96, s0
	v_lshl_add_u32 v17, v17, 1, v124
	ds_write_b16 v17, v60

; __device__ __forceinline__ void unpack8(const u32x4 w, float* f) { f[0] = bflo(w.x); f[1] = bfhi(w.x); f[2] = bflo(w.y); f[3] = bfhi(w.y); f[4] = bflo(w.z); f[5] = bfhi(w.z); f[6] = bflo(w.w); f[7] = bfhi(w.w); }
; #define SSD_LD(tt) ((live && (tt) >= 0) ? *(const u32x4*)(PJ + (size_t)tok_row(b, (tt)) * PW + C_XBC + xcol) : (u32x4){0u, 0u, 0u, 0u})
; template <bool PASSA> __device__ __forceinline__ void ssd_stage(const Ptrs& P, int l, int b, int ch, int gg, unsigned char* lds, int tid) {
;     ...
;         { const u32x4 h0 = SSD_LD(t0 - 3), h1 = SSD_LD(t0 - 2), h2 = SSD_LD(t0 - 1); unpack8(h0, x0); unpack8(h1, x1); unpack8(h2, x2); }
;         u32x4 n0 = SSD_LD(t0), n1 = SSD_LD(t0 + 1), n2 = SSD_LD(t0 + 2), n3 = SSD_LD(t0 + 3);
; #pragma unroll 1
;         for (int i = 0; i < 16; ++i) {
;             const int li = l0 + i;
;             unpack8(n0, x3); n0 = n1; n1 = n2; n2 = n3; n3 = (i + 4 < 16) ? SSD_LD(t0 + i + 4) : (u32x4){0u, 0u, 0u, 0u};
.Lsb_top_4:
	v_mov_b64_e32 v[88:89], v[82:83]
	v_mov_b64_e32 v[82:83], v[18:19]
	s_cmp_lt_u32 s17, 12
	v_mov_b32_e32 v18, v16
	v_mov_b32_e32 v19, v16
	s_cselect_b64 s[6:7], -1, 0
	v_mov_b32_e32 v17, v16
	v_mov_b64_e32 v[62:63], v[18:19]
	v_mov_b64_e32 v[90:91], v[72:73]
	v_mov_b64_e32 v[72:73], v[84:85]
	v_mov_b64_e32 v[92:93], v[76:77]
	v_mov_b64_e32 v[76:77], v[86:87]
	v_mov_b64_e32 v[94:95], v[74:75]
	v_mov_b64_e32 v[74:75], v[78:79]
	s_and_b64 s[8:9], s[44:45], s[6:7]
	v_mov_b64_e32 v[60:61], v[16:17]
	s_and_saveexec_b64 s[6:7], s[8:9]
	s_cbranch_execz .Lsb4_930
	v_mov_b32_e32 v18, v16
	v_mov_b32_e32 v19, v16
	v_add_u32_e32 v78, s17, v108
	v_mov_b32_e32 v17, v16
	v_mov_b64_e32 v[62:63], v[18:19]
	v_cmp_lt_i32_e32 vcc, -5, v78
	v_mov_b64_e32 v[60:61], v[16:17]
	s_and_saveexec_b64 s[8:9], vcc
	s_cbranch_execz .Lsb4_929
	v_add_u32_e32 v17, 4, v78
	v_cmp_gt_u32_e32 vcc, 16, v17
	s_nop 1
	v_cndmask_b32_e32 v17, v126, v125, vcc
	v_add_u32_e32 v17, s17, v17
	v_mad_i64_i32 v[18:19], s[20:21], v17, s34, v[160:161]
	v_lshl_add_u64 v[18:19], v[80:81], 1, v[18:19]
	v_add_co_u32_e32 v18, vcc, 0x1000, v18
	s_nop 1
	v_addc_co_u32_e32 v19, vcc, 0, v19, vcc
	global_load_dwordx4 v[60:63], v[18:19], off offset:2560

; __device__ __forceinline__ unsigned pk2(float lo, float hi) { f32x2_t v = {lo, hi}; bf16x2_t b = __builtin_convertvector(v, bf16x2_t); return __builtin_bit_cast(unsigned, b); }
; __device__ __forceinline__ unsigned f2bf(float f) { return pk2(f, 0.f) & 0xffffu; }
; __device__ __forceinline__ float siluf(float x) { return x * __builtin_amdgcn_rcpf(1.0f + __expf(-x)); }
; __device__ __forceinline__ void unpack8(const u32x4 w, float* f) { f[0] = bflo(w.x); f[1] = bfhi(w.x); f[2] = bflo(w.y); f[3] = bfhi(w.y); f[4] = bflo(w.z); f[5] = bfhi(w.z); f[6] = bflo(w.w); f[7] = bfhi(w.w); }
; #define SSD_LD(tt) ((live && (tt) >= 0) ? *(const u32x4*)(PJ + (size_t)tok_row(b, (tt)) * PW + C_XBC + xcol) : (u32x4){0u, 0u, 0u, 0u})
; template <bool PASSA> __device__ __forceinline__ void ssd_stage(const Ptrs& P, int l, int b, int ch, int gg, unsigned char* lds, int tid) {
;     ...
;             unpack8(n0, x3); n0 = n1; n1 = n2; n2 = n3; n3 = (i + 4 < 16) ? SSD_LD(t0 + i + 4) : (u32x4){0u, 0u, 0u, 0u};
;             float o[8];
; #pragma unroll
;             for (int e = 0; e < 8; ++e) { float v = bias[e] + wgt[0][e] * x0[e] + wgt[1][e] * x1[e] + wgt[2][e] * x2[e] + wgt[3][e] * x3[e]; v = siluf(v); o[e] = (li < nvalid) ? v : 0.f;
;                 x0[e] = x1[e]; x1[e] = x2[e]; x2[e] = x3[e]; }
;             if (kind == 0) {
; #pragma unroll
;                 for (int e = 0; e < 8; ++e) Xt[sdz(i0 + e, li)] = (bf16_t)f2bf(o[e]);
;             } else if (kind == 1) {
;                 if (PASSA) {
; #pragma unroll
;                     for (int e = 0; e < 8; ++e) Bs[sdz(i0 + e, li)] = (bf16_t)f2bf(o[e]);
;                 } else { u32x4 wv; wv.x = pk2(o[0], o[1]); wv.y = pk2(o[2], o[3]); wv.z = pk2(o[4], o[5]); wv.w = pk2(o[6], o[7]); *(u32x4*)(Bs + li * 136 + i0) = wv; }
;             } else { u32x4 wv; wv.x = pk2(o[0], o[1]); wv.y = pk2(o[2], o[3]); wv.z = pk2(o[4], o[5]); wv.w = pk2(o[6], o[7]); *(u32x4*)(Cs + li * 136 + i0) = wv; }
.Lsb4_930:
	s_or_b64 exec, exec, s[6:7]
	v_lshlrev_b32_e32 v18, 16, v64
	v_and_b32_e32 v19, 0xffff0000, v64
	v_lshlrev_b32_e32 v84, 16, v65
	v_and_b32_e32 v85, 0xffff0000, v65
	v_pk_fma_f32 v[64:65], v[12:13], v[102:103], v[48:49]
	v_lshlrev_b32_e32 v86, 16, v66
	v_pk_fma_f32 v[64:65], v[20:21], v[88:89], v[64:65]
	v_and_b32_e32 v87, 0xffff0000, v66
	v_pk_fma_f32 v[64:65], v[28:29], v[82:83], v[64:65]
	v_lshlrev_b32_e32 v78, 16, v67
	v_pk_fma_f32 v[64:65], v[36:37], v[18:19], v[64:65]
	v_and_b32_e32 v79, 0xffff0000, v67
	v_mul_f32_e32 v66, 0xbfb8aa3b, v64
	v_mul_f32_e32 v67, 0xbfb8aa3b, v65
	v_exp_f32_e32 v66, v66
	v_exp_f32_e32 v67, v67
	v_add_u32_e32 v17, s17, v107
	v_cmp_gt_i32_e32 vcc, s14, v17
	v_add_f32_e32 v66, 1.0, v66
	v_add_f32_e32 v67, 1.0, v67
	v_rcp_f32_e32 v66, v66
	v_rcp_f32_e32 v67, v67
	v_pk_fma_f32 v[98:99], v[8:9], v[98:99], v[44:45]
	v_pk_fma_f32 v[96:97], v[10:11], v[96:97], v[46:47]
	v_pk_fma_f32 v[98:99], v[24:25], v[92:93], v[98:99]
	v_pk_mul_f32 v[66:67], v[64:65], v[66:67]
	v_pk_fma_f32 v[98:99], v[32:33], v[76:77], v[98:99]
	v_cndmask_b32_e32 v64, 0, v67, vcc
	v_cndmask_b32_e32 v65, 0, v66, vcc
	v_pk_fma_f32 v[66:67], v[14:15], v[100:101], v[50:51]
	v_pk_fma_f32 v[98:99], v[40:41], v[86:87], v[98:99]
	v_pk_fma_f32 v[66:67], v[22:23], v[90:91], v[66:67]
	v_pk_fma_f32 v[96:97], v[26:27], v[94:95], v[96:97]
	v_pk_fma_f32 v[66:67], v[30:31], v[72:73], v[66:67]
	v_pk_fma_f32 v[96:97], v[34:35], v[74:75], v[96:97]
	v_pk_fma_f32 v[66:67], v[38:39], v[84:85], v[66:67]
	v_pk_fma_f32 v[96:97], v[42:43], v[78:79], v[96:97]
	v_mul_f32_e32 v100, 0xbfb8aa3b, v66
	v_mul_f32_e32 v101, 0xbfb8aa3b, v67
	v_exp_f32_e32 v100, v100
	v_exp_f32_e32 v101, v101
	v_add_f32_e32 v100, 1.0, v100
	v_add_f32_e32 v101, 1.0, v101
	v_rcp_f32_e32 v100, v100
	v_rcp_f32_e32 v101, v101
	s_nop 0
	v_pk_mul_f32 v[100:101], v[66:67], v[100:101]
	s_nop 0
	v_cndmask_b32_e32 v66, 0, v101, vcc
	v_cndmask_b32_e32 v67, 0, v100, vcc
	v_mul_f32_e32 v100, 0xbfb8aa3b, v98
	v_mul_f32_e32 v101, 0xbfb8aa3b, v99
	v_exp_f32_e32 v100, v100
	v_exp_f32_e32 v101, v101
	v_add_f32_e32 v100, 1.0, v100
	v_add_f32_e32 v101, 1.0, v101
	v_rcp_f32_e32 v100, v100
	v_rcp_f32_e32 v101, v101
	s_nop 0
	v_pk_mul_f32 v[100:101], v[98:99], v[100:101]
	s_nop 0
	v_cndmask_b32_e32 v98, 0, v101, vcc
	v_cndmask_b32_e32 v99, 0, v100, vcc
	v_mul_f32_e32 v100, 0xbfb8aa3b, v96
	v_mul_f32_e32 v101, 0xbfb8aa3b, v97
	v_exp_f32_e32 v100, v100
	v_exp_f32_e32 v101, v101
	v_add_f32_e32 v100, 1.0, v100
	v_add_f32_e32 v101, 1.0, v101
	v_rcp_f32_e32 v100, v100
	v_rcp_f32_e32 v101, v101
	s_nop 0
	v_pk_mul_f32 v[100:101], v[96:97], v[100:101]
	s_nop 0
	v_cndmask_b32_e32 v96, 0, v101, vcc
	v_cndmask_b32_e32 v97, 0, v100, vcc
	s_and_saveexec_b64 s[6:7], s[42:43]
	s_xor_b64 s[6:7], exec, s[6:7]
	s_cbranch_execz .Lsb4_936
	v_cvt_pk_bf16_f32 v64, v65, v64
	v_cvt_pk_bf16_f32 v65, v67, v66
	v_cvt_pk_bf16_f32 v66, v99, v98
	v_cvt_pk_bf16_f32 v67, v97, v96
	s_and_saveexec_b64 s[8:9], s[4:5]
	s_xor_b64 s[8:9], exec, s[8:9]
	ds_write_b128 v127, v[64:67] offset:34816
	s_andn2_saveexec_b64 s[8:9], s[8:9]
	ds_write_b128 v127, v[64:67]
	s_or_b64 exec, exec, s[8:9]
.Lsb4_936:
	s_andn2_saveexec_b64 s[6:7], s[6:7]
	s_cbranch_execz .Lsb_bot_4
	v_xor_b32_e32 v100, v17, v109
	v_cvt_pk_bf16_f32 v65, v65, s0
	v_lshl_add_u32 v100, v100, 1, v110
	ds_write_b16 v100, v65
	v_xor_b32_e32 v65, v17, v111
	v_cvt_pk_bf16_f32 v64, v64, s0
	v_lshl_add_u32 v65, v65, 1, v112
	ds_write_b16 v65, v64
	v_xor_b32_e32 v65, v17, v113
	v_cvt_pk_bf16_f32 v64, v67, s0
	v_lshl_add_u32 v65, v65, 1, v114
	ds_write_b16 v65, v64
	v_xor_b32_e32 v65, v17, v115
	v_cvt_pk_bf16_f32 v64, v66, s0
	v_lshl_add_u32 v65, v65, 1, v116
	ds_write_b16 v65, v64
	v_xor_b32_e32 v65, v17, v117
	v_cvt_pk_bf16_f32 v64, v99, s0
	v_lshl_add_u32 v65, v65, 1, v118
	ds_write_b16 v65, v64
	v_xor_b32_e32 v65, v17, v119
	v_cvt_pk_bf16_f32 v64, v98, s0
	v_lshl_add_u32 v65, v65, 1, v120
	ds_write_b16 v65, v64
	v_xor_b32_e32 v65, v17, v121
	v_cvt_pk_bf16_f32 v64, v97, s0
	v_lshl_add_u32 v65, v65, 1, v122
	v_xor_b32_e32 v17, v17, v123
	ds_write_b16 v65, v64
	v_cvt_pk_bf16_f32 v64, v96, s0
	v_lshl_add_u32 v17, v17, 1, v124
	ds_write_b16 v17, v64
